# prompt conv LayerNorm statistics: 32 serial DPP wave-sum chains (s_nop padded) replaced by interleaved in-place DPP adds
# speedup vs baseline: 1.1203x; 1.0018x over previous
; #define LAS __attribute__((address_space(3)))
; __device__ __forceinline__ float bf_lo(unsigned w) { return __uint_as_float(w << 16); }
; __device__ __forceinline__ float bf_hi(unsigned w) { return __uint_as_float(w & 0xffff0000u); }
; __device__ __forceinline__ void p2_conv_unit_prompt(Frame& F, int unit, int next_pm, const ConvW& cw, size_t src_off = WS_A, size_t dst_off = WS_CACT) {
;     ...
; #pragma unroll
;         for (int rg = 0; rg < CV_ROWS; rg += 8) {
;             unsigned w2[8], w1[8];
; #pragma unroll
;             for (int i = 0; i < 8; ++i) if (rg + i < CV_ROWS) { const LAS unsigned char* rp = S + (rg + i) * (DCONV * 2) + ((rg + i) < CW - 1 ? ringLo : ringHi);
;                 w2[i] = *(const LAS unsigned*)(rp + p * 2u); w1[i] = *(const LAS unsigned short*)(rp + q * 2u); }
; #pragma unroll
;             for (int i = 0; i < 8; ++i) if (rg + i < CV_ROWS) { const int rr = rg + i; const f32x2 vp = (f32x2){bf_lo(w2[i]), bf_hi(w2[i])}; const float vq = bf_lo(w1[i]);
; #pragma unroll
;                 for (int t = 0; t < 16; ++t) { const int j = rr - t; if (j >= 0 && j < CW) { ap[t] += wp[j] * vp; aq[t] += wq[j] * vq; } } }
;             __builtin_amdgcn_sched_barrier(0); }
.LBB0_480:
	v_lshlrev_b32_e32 v1, 16, v145
	v_lshlrev_b32_e32 v38, 16, v36
	v_and_b32_e32 v39, 0xffff0000, v36
	v_pk_fma_f32 v[38:39], v[114:115], v[38:39], v[120:121]
	v_fma_f32 v145, v190, v1, v197
	v_lshlrev_b32_e32 v36, 16, v37
	v_and_b32_e32 v37, 0xffff0000, v37
	v_lshlrev_b32_e32 v1, 16, v144
	v_pk_fma_f32 v[38:39], v[116:117], v[36:37], v[38:39]
	v_fmac_f32_e32 v145, v191, v1
	v_pk_fma_f32 v[36:37], v[114:115], v[36:37], v[120:121]
	v_fma_f32 v144, v190, v1, v197
	v_lshlrev_b32_e32 v230, 16, v34
	v_and_b32_e32 v231, 0xffff0000, v34
	v_lshlrev_b32_e32 v1, 16, v143
	v_pk_fma_f32 v[38:39], v[118:119], v[230:231], v[38:39]
	v_fmac_f32_e32 v145, v192, v1
	v_pk_fma_f32 v[36:37], v[116:117], v[230:231], v[36:37]
	v_fmac_f32_e32 v144, v191, v1
	v_pk_fma_f32 v[230:231], v[114:115], v[230:231], v[120:121]
	v_fma_f32 v143, v190, v1, v197
	v_lshlrev_b32_e32 v34, 16, v35
	v_and_b32_e32 v35, 0xffff0000, v35
	v_lshlrev_b32_e32 v1, 16, v142
	v_pk_fma_f32 v[38:39], v[58:59], v[34:35], v[38:39]
	v_fmac_f32_e32 v145, v193, v1
	v_pk_fma_f32 v[36:37], v[118:119], v[34:35], v[36:37]
	v_fmac_f32_e32 v144, v192, v1
	v_pk_fma_f32 v[230:231], v[116:117], v[34:35], v[230:231]
	v_fmac_f32_e32 v143, v191, v1
	v_pk_fma_f32 v[34:35], v[114:115], v[34:35], v[120:121]
	v_fma_f32 v142, v190, v1, v197
	v_lshlrev_b32_e32 v232, 16, v32
	v_and_b32_e32 v233, 0xffff0000, v32
	v_lshlrev_b32_e32 v1, 16, v141
	v_pk_fma_f32 v[38:39], v[60:61], v[232:233], v[38:39]
	v_fmac_f32_e32 v145, v194, v1
	v_pk_fma_f32 v[36:37], v[58:59], v[232:233], v[36:37]
	v_fmac_f32_e32 v144, v193, v1
	v_pk_fma_f32 v[230:231], v[118:119], v[232:233], v[230:231]
	v_fmac_f32_e32 v143, v192, v1
	v_pk_fma_f32 v[34:35], v[116:117], v[232:233], v[34:35]
	v_fmac_f32_e32 v142, v191, v1
	v_pk_fma_f32 v[232:233], v[114:115], v[232:233], v[120:121]
	v_fma_f32 v141, v190, v1, v197
	v_lshlrev_b32_e32 v32, 16, v33
	v_and_b32_e32 v33, 0xffff0000, v33
	v_lshlrev_b32_e32 v1, 16, v140
	v_pk_fma_f32 v[38:39], v[62:63], v[32:33], v[38:39]
	v_fmac_f32_e32 v145, v195, v1
	v_pk_fma_f32 v[36:37], v[60:61], v[32:33], v[36:37]
	v_fmac_f32_e32 v144, v194, v1
	v_pk_fma_f32 v[230:231], v[58:59], v[32:33], v[230:231]
	v_fmac_f32_e32 v143, v193, v1
	v_pk_fma_f32 v[34:35], v[118:119], v[32:33], v[34:35]
	v_fmac_f32_e32 v142, v192, v1
	v_pk_fma_f32 v[232:233], v[116:117], v[32:33], v[232:233]
	v_fmac_f32_e32 v141, v191, v1
	v_pk_fma_f32 v[32:33], v[114:115], v[32:33], v[120:121]
	v_fma_f32 v140, v190, v1, v197
	v_lshlrev_b32_e32 v234, 16, v30
	v_and_b32_e32 v235, 0xffff0000, v30
	v_lshlrev_b32_e32 v1, 16, v139
	v_pk_fma_f32 v[38:39], v[64:65], v[234:235], v[38:39]
	v_fmac_f32_e32 v145, v196, v1
	v_pk_fma_f32 v[36:37], v[62:63], v[234:235], v[36:37]
	v_fmac_f32_e32 v144, v195, v1
	v_pk_fma_f32 v[230:231], v[60:61], v[234:235], v[230:231]
	v_fmac_f32_e32 v143, v194, v1
	v_pk_fma_f32 v[34:35], v[58:59], v[234:235], v[34:35]
	v_fmac_f32_e32 v142, v193, v1
	v_pk_fma_f32 v[232:233], v[118:119], v[234:235], v[232:233]
	v_fmac_f32_e32 v141, v192, v1
	v_pk_fma_f32 v[32:33], v[116:117], v[234:235], v[32:33]
	v_fmac_f32_e32 v140, v191, v1
	v_pk_fma_f32 v[234:235], v[114:115], v[234:235], v[120:121]
	v_fma_f32 v139, v190, v1, v197
	v_lshlrev_b32_e32 v30, 16, v31
	v_and_b32_e32 v31, 0xffff0000, v31
	v_lshlrev_b32_e32 v1, 16, v138
	v_pk_fma_f32 v[38:39], v[66:67], v[30:31], v[38:39]
	v_fmac_f32_e32 v145, v166, v1
	v_pk_fma_f32 v[36:37], v[64:65], v[30:31], v[36:37]
	v_fmac_f32_e32 v144, v196, v1
	v_pk_fma_f32 v[230:231], v[62:63], v[30:31], v[230:231]
	v_fmac_f32_e32 v143, v195, v1
	v_pk_fma_f32 v[34:35], v[60:61], v[30:31], v[34:35]
	v_fmac_f32_e32 v142, v194, v1
	v_pk_fma_f32 v[232:233], v[58:59], v[30:31], v[232:233]
	v_fmac_f32_e32 v141, v193, v1
	v_pk_fma_f32 v[32:33], v[118:119], v[30:31], v[32:33]
	v_fmac_f32_e32 v140, v192, v1
	v_pk_fma_f32 v[234:235], v[116:117], v[30:31], v[234:235]
	v_fmac_f32_e32 v139, v191, v1
	v_pk_fma_f32 v[30:31], v[114:115], v[30:31], v[120:121]
	v_fma_f32 v138, v190, v1, v197
	v_lshlrev_b32_e32 v236, 16, v28
	v_and_b32_e32 v237, 0xffff0000, v28
	v_lshlrev_b32_e32 v1, 16, v137
	v_pk_fma_f32 v[38:39], v[68:69], v[236:237], v[38:39]
	v_fmac_f32_e32 v145, v167, v1
	v_pk_fma_f32 v[36:37], v[66:67], v[236:237], v[36:37]
	v_fmac_f32_e32 v144, v166, v1
	v_pk_fma_f32 v[230:231], v[64:65], v[236:237], v[230:231]
	v_fmac_f32_e32 v143, v196, v1
	v_pk_fma_f32 v[34:35], v[62:63], v[236:237], v[34:35]
	v_fmac_f32_e32 v142, v195, v1
	v_pk_fma_f32 v[232:233], v[60:61], v[236:237], v[232:233]
	v_fmac_f32_e32 v141, v194, v1
	v_pk_fma_f32 v[32:33], v[58:59], v[236:237], v[32:33]
	v_fmac_f32_e32 v140, v193, v1
	v_pk_fma_f32 v[234:235], v[118:119], v[236:237], v[234:235]
	v_fmac_f32_e32 v139, v192, v1
	v_pk_fma_f32 v[30:31], v[116:117], v[236:237], v[30:31]
	v_fmac_f32_e32 v138, v191, v1
	v_pk_fma_f32 v[236:237], v[114:115], v[236:237], v[120:121]
	v_fma_f32 v137, v190, v1, v197
	v_lshlrev_b32_e32 v28, 16, v29
	v_and_b32_e32 v29, 0xffff0000, v29
	v_lshlrev_b32_e32 v1, 16, v136
	v_pk_fma_f32 v[38:39], v[70:71], v[28:29], v[38:39]
	v_fmac_f32_e32 v145, v168, v1
	v_pk_fma_f32 v[36:37], v[68:69], v[28:29], v[36:37]
	v_fmac_f32_e32 v144, v167, v1
	v_pk_fma_f32 v[230:231], v[66:67], v[28:29], v[230:231]
	v_fmac_f32_e32 v143, v166, v1
	v_pk_fma_f32 v[34:35], v[64:65], v[28:29], v[34:35]
	v_fmac_f32_e32 v142, v196, v1
	v_pk_fma_f32 v[232:233], v[62:63], v[28:29], v[232:233]
	v_fmac_f32_e32 v141, v195, v1
	v_pk_fma_f32 v[32:33], v[60:61], v[28:29], v[32:33]
	v_fmac_f32_e32 v140, v194, v1
	v_pk_fma_f32 v[234:235], v[58:59], v[28:29], v[234:235]
	v_fmac_f32_e32 v139, v193, v1
	v_pk_fma_f32 v[30:31], v[118:119], v[28:29], v[30:31]
; #define LAS __attribute__((address_space(3)))
; __device__ __forceinline__ float bf_lo(unsigned w) { return __uint_as_float(w << 16); }
; __device__ __forceinline__ float bf_hi(unsigned w) { return __uint_as_float(w & 0xffff0000u); }
; __device__ __forceinline__ void p2_conv_unit_prompt(Frame& F, int unit, int next_pm, const ConvW& cw, size_t src_off = WS_A, size_t dst_off = WS_CACT) {
;     ...
; #pragma unroll
;         for (int rg = 0; rg < CV_ROWS; rg += 8) {
;             unsigned w2[8], w1[8];
; #pragma unroll
;             for (int i = 0; i < 8; ++i) if (rg + i < CV_ROWS) { const LAS unsigned char* rp = S + (rg + i) * (DCONV * 2) + ((rg + i) < CW - 1 ? ringLo : ringHi);
;                 w2[i] = *(const LAS unsigned*)(rp + p * 2u); w1[i] = *(const LAS unsigned short*)(rp + q * 2u); }
; #pragma unroll
;             for (int i = 0; i < 8; ++i) if (rg + i < CV_ROWS) { const int rr = rg + i; const f32x2 vp = (f32x2){bf_lo(w2[i]), bf_hi(w2[i])}; const float vq = bf_lo(w1[i]);
; #pragma unroll
;                 for (int t = 0; t < 16; ++t) { const int j = rr - t; if (j >= 0 && j < CW) { ap[t] += wp[j] * vp; aq[t] += wq[j] * vq; } } }
;             __builtin_amdgcn_sched_barrier(0); }
	v_fmac_f32_e32 v138, v192, v1
	v_pk_fma_f32 v[236:237], v[116:117], v[28:29], v[236:237]
	v_fmac_f32_e32 v137, v191, v1
	v_pk_fma_f32 v[28:29], v[114:115], v[28:29], v[120:121]
	v_fma_f32 v136, v190, v1, v197
	v_lshlrev_b32_e32 v238, 16, v26
	v_and_b32_e32 v239, 0xffff0000, v26
	v_lshlrev_b32_e32 v1, 16, v135
	v_pk_fma_f32 v[38:39], v[72:73], v[238:239], v[38:39]
	v_fmac_f32_e32 v145, v169, v1
	v_pk_fma_f32 v[36:37], v[70:71], v[238:239], v[36:37]
	v_fmac_f32_e32 v144, v168, v1
	v_pk_fma_f32 v[230:231], v[68:69], v[238:239], v[230:231]
	v_fmac_f32_e32 v143, v167, v1
	v_pk_fma_f32 v[34:35], v[66:67], v[238:239], v[34:35]
	v_fmac_f32_e32 v142, v166, v1
	v_pk_fma_f32 v[232:233], v[64:65], v[238:239], v[232:233]
	v_fmac_f32_e32 v141, v196, v1
	v_pk_fma_f32 v[32:33], v[62:63], v[238:239], v[32:33]
	v_fmac_f32_e32 v140, v195, v1
	v_pk_fma_f32 v[234:235], v[60:61], v[238:239], v[234:235]
	v_fmac_f32_e32 v139, v194, v1
	v_pk_fma_f32 v[30:31], v[58:59], v[238:239], v[30:31]
	v_fmac_f32_e32 v138, v193, v1
	v_pk_fma_f32 v[236:237], v[118:119], v[238:239], v[236:237]
	v_fmac_f32_e32 v137, v192, v1
	v_pk_fma_f32 v[28:29], v[116:117], v[238:239], v[28:29]
	v_fmac_f32_e32 v136, v191, v1
	v_pk_fma_f32 v[238:239], v[114:115], v[238:239], v[120:121]
	v_fma_f32 v135, v190, v1, v197
	v_lshlrev_b32_e32 v26, 16, v27
	v_and_b32_e32 v27, 0xffff0000, v27
	v_lshlrev_b32_e32 v1, 16, v134
	v_pk_fma_f32 v[38:39], v[74:75], v[26:27], v[38:39]
	v_fmac_f32_e32 v145, v170, v1
	v_pk_fma_f32 v[36:37], v[72:73], v[26:27], v[36:37]
	v_fmac_f32_e32 v144, v169, v1
	v_pk_fma_f32 v[230:231], v[70:71], v[26:27], v[230:231]
	v_fmac_f32_e32 v143, v168, v1
	v_pk_fma_f32 v[34:35], v[68:69], v[26:27], v[34:35]
	v_fmac_f32_e32 v142, v167, v1
	v_pk_fma_f32 v[232:233], v[66:67], v[26:27], v[232:233]
	v_fmac_f32_e32 v141, v166, v1
	v_pk_fma_f32 v[32:33], v[64:65], v[26:27], v[32:33]
	v_fmac_f32_e32 v140, v196, v1
	v_pk_fma_f32 v[234:235], v[62:63], v[26:27], v[234:235]
	v_fmac_f32_e32 v139, v195, v1
	v_pk_fma_f32 v[30:31], v[60:61], v[26:27], v[30:31]
	v_fmac_f32_e32 v138, v194, v1
	v_pk_fma_f32 v[236:237], v[58:59], v[26:27], v[236:237]
	v_fmac_f32_e32 v137, v193, v1
	v_pk_fma_f32 v[28:29], v[118:119], v[26:27], v[28:29]
	v_fmac_f32_e32 v136, v192, v1
	v_pk_fma_f32 v[238:239], v[116:117], v[26:27], v[238:239]
	v_fmac_f32_e32 v135, v191, v1
	v_pk_fma_f32 v[26:27], v[114:115], v[26:27], v[120:121]
	v_fma_f32 v134, v190, v1, v197
	v_lshlrev_b32_e32 v240, 16, v24
	v_and_b32_e32 v241, 0xffff0000, v24
	v_lshlrev_b32_e32 v1, 16, v133
	v_pk_fma_f32 v[38:39], v[76:77], v[240:241], v[38:39]
	v_fmac_f32_e32 v145, v171, v1
	v_pk_fma_f32 v[36:37], v[74:75], v[240:241], v[36:37]
	v_fmac_f32_e32 v144, v170, v1
	v_pk_fma_f32 v[230:231], v[72:73], v[240:241], v[230:231]
	v_fmac_f32_e32 v143, v169, v1
	v_pk_fma_f32 v[34:35], v[70:71], v[240:241], v[34:35]
	v_fmac_f32_e32 v142, v168, v1
	v_pk_fma_f32 v[232:233], v[68:69], v[240:241], v[232:233]
	v_fmac_f32_e32 v141, v167, v1
	v_pk_fma_f32 v[32:33], v[66:67], v[240:241], v[32:33]
	v_fmac_f32_e32 v140, v166, v1
	v_pk_fma_f32 v[234:235], v[64:65], v[240:241], v[234:235]
	v_fmac_f32_e32 v139, v196, v1
	v_pk_fma_f32 v[30:31], v[62:63], v[240:241], v[30:31]
	v_fmac_f32_e32 v138, v195, v1
	v_pk_fma_f32 v[236:237], v[60:61], v[240:241], v[236:237]
	v_fmac_f32_e32 v137, v194, v1
	v_pk_fma_f32 v[28:29], v[58:59], v[240:241], v[28:29]
	v_fmac_f32_e32 v136, v193, v1
	v_pk_fma_f32 v[238:239], v[118:119], v[240:241], v[238:239]
	v_fmac_f32_e32 v135, v192, v1
	v_pk_fma_f32 v[26:27], v[116:117], v[240:241], v[26:27]
	v_fmac_f32_e32 v134, v191, v1
	v_pk_fma_f32 v[240:241], v[114:115], v[240:241], v[120:121]
	v_fma_f32 v133, v190, v1, v197
	v_lshlrev_b32_e32 v24, 16, v25
	v_and_b32_e32 v25, 0xffff0000, v25
	v_lshlrev_b32_e32 v1, 16, v5
	v_pk_fma_f32 v[38:39], v[78:79], v[24:25], v[38:39]
	v_fmac_f32_e32 v145, v172, v1
	v_pk_fma_f32 v[36:37], v[76:77], v[24:25], v[36:37]
	v_fmac_f32_e32 v144, v171, v1
	v_pk_fma_f32 v[230:231], v[74:75], v[24:25], v[230:231]
	v_fmac_f32_e32 v143, v170, v1
	v_pk_fma_f32 v[34:35], v[72:73], v[24:25], v[34:35]
	v_fmac_f32_e32 v142, v169, v1
	v_pk_fma_f32 v[232:233], v[70:71], v[24:25], v[232:233]
	v_fmac_f32_e32 v141, v168, v1
	v_pk_fma_f32 v[32:33], v[68:69], v[24:25], v[32:33]
	v_fmac_f32_e32 v140, v167, v1
	v_pk_fma_f32 v[234:235], v[66:67], v[24:25], v[234:235]
	v_fmac_f32_e32 v139, v166, v1
	v_pk_fma_f32 v[30:31], v[64:65], v[24:25], v[30:31]
	v_fmac_f32_e32 v138, v196, v1
	v_pk_fma_f32 v[236:237], v[62:63], v[24:25], v[236:237]
	v_fmac_f32_e32 v137, v195, v1
	v_pk_fma_f32 v[28:29], v[60:61], v[24:25], v[28:29]
	v_fmac_f32_e32 v136, v194, v1
	v_pk_fma_f32 v[238:239], v[58:59], v[24:25], v[238:239]
	v_fmac_f32_e32 v135, v193, v1
	v_pk_fma_f32 v[26:27], v[118:119], v[24:25], v[26:27]
	v_fmac_f32_e32 v134, v192, v1
	v_pk_fma_f32 v[240:241], v[116:117], v[24:25], v[240:241]
	v_fmac_f32_e32 v133, v191, v1
	v_pk_fma_f32 v[24:25], v[114:115], v[24:25], v[120:121]
	v_fma_f32 v5, v190, v1, v197
	v_lshlrev_b32_e32 v242, 16, v22
	v_and_b32_e32 v243, 0xffff0000, v22
	v_lshlrev_b32_e32 v1, 16, v225
	v_pk_fma_f32 v[38:39], v[80:81], v[242:243], v[38:39]
	v_fmac_f32_e32 v145, v173, v1
	v_pk_fma_f32 v[36:37], v[78:79], v[242:243], v[36:37]
	v_fmac_f32_e32 v144, v172, v1
	v_pk_fma_f32 v[230:231], v[76:77], v[242:243], v[230:231]
	v_fmac_f32_e32 v143, v171, v1
	v_pk_fma_f32 v[34:35], v[74:75], v[242:243], v[34:35]
	v_fmac_f32_e32 v142, v170, v1
	v_pk_fma_f32 v[232:233], v[72:73], v[242:243], v[232:233]
	v_fmac_f32_e32 v141, v169, v1
	v_pk_fma_f32 v[32:33], v[70:71], v[242:243], v[32:33]
	v_fmac_f32_e32 v140, v168, v1
	v_pk_fma_f32 v[234:235], v[68:69], v[242:243], v[234:235]
; #define LAS __attribute__((address_space(3)))
; __device__ __forceinline__ float bf_lo(unsigned w) { return __uint_as_float(w << 16); }
; __device__ __forceinline__ float bf_hi(unsigned w) { return __uint_as_float(w & 0xffff0000u); }
; __device__ __forceinline__ void p2_conv_unit_prompt(Frame& F, int unit, int next_pm, const ConvW& cw, size_t src_off = WS_A, size_t dst_off = WS_CACT) {
;     ...
; #pragma unroll
;         for (int rg = 0; rg < CV_ROWS; rg += 8) {
;             unsigned w2[8], w1[8];
; #pragma unroll
;             for (int i = 0; i < 8; ++i) if (rg + i < CV_ROWS) { const LAS unsigned char* rp = S + (rg + i) * (DCONV * 2) + ((rg + i) < CW - 1 ? ringLo : ringHi);
;                 w2[i] = *(const LAS unsigned*)(rp + p * 2u); w1[i] = *(const LAS unsigned short*)(rp + q * 2u); }
; #pragma unroll
;             for (int i = 0; i < 8; ++i) if (rg + i < CV_ROWS) { const int rr = rg + i; const f32x2 vp = (f32x2){bf_lo(w2[i]), bf_hi(w2[i])}; const float vq = bf_lo(w1[i]);
; #pragma unroll
;                 for (int t = 0; t < 16; ++t) { const int j = rr - t; if (j >= 0 && j < CW) { ap[t] += wp[j] * vp; aq[t] += wq[j] * vq; } } }
;             __builtin_amdgcn_sched_barrier(0); }
	v_fmac_f32_e32 v139, v167, v1
	v_pk_fma_f32 v[30:31], v[66:67], v[242:243], v[30:31]
	v_fmac_f32_e32 v138, v166, v1
	v_pk_fma_f32 v[236:237], v[64:65], v[242:243], v[236:237]
	v_fmac_f32_e32 v137, v196, v1
	v_pk_fma_f32 v[28:29], v[62:63], v[242:243], v[28:29]
	v_fmac_f32_e32 v136, v195, v1
	v_pk_fma_f32 v[238:239], v[60:61], v[242:243], v[238:239]
	v_fmac_f32_e32 v135, v194, v1
	v_pk_fma_f32 v[26:27], v[58:59], v[242:243], v[26:27]
	v_fmac_f32_e32 v134, v193, v1
	v_pk_fma_f32 v[240:241], v[118:119], v[242:243], v[240:241]
	v_fmac_f32_e32 v133, v192, v1
	v_pk_fma_f32 v[24:25], v[116:117], v[242:243], v[24:25]
	v_fmac_f32_e32 v5, v191, v1
	v_pk_fma_f32 v[242:243], v[114:115], v[242:243], v[120:121]
	v_fma_f32 v2, v190, v1, v197
	v_lshlrev_b32_e32 v22, 16, v23
	v_and_b32_e32 v23, 0xffff0000, v23
	v_lshlrev_b32_e32 v1, 16, v7
	v_pk_fma_f32 v[38:39], v[82:83], v[22:23], v[38:39]
	v_fmac_f32_e32 v145, v174, v1
	v_pk_fma_f32 v[36:37], v[80:81], v[22:23], v[36:37]
	v_fmac_f32_e32 v144, v173, v1
	v_pk_fma_f32 v[230:231], v[78:79], v[22:23], v[230:231]
	v_fmac_f32_e32 v143, v172, v1
	v_pk_fma_f32 v[34:35], v[76:77], v[22:23], v[34:35]
	v_fmac_f32_e32 v142, v171, v1
	v_pk_fma_f32 v[232:233], v[74:75], v[22:23], v[232:233]
	v_fmac_f32_e32 v141, v170, v1
	v_pk_fma_f32 v[32:33], v[72:73], v[22:23], v[32:33]
	v_fmac_f32_e32 v140, v169, v1
	v_pk_fma_f32 v[234:235], v[70:71], v[22:23], v[234:235]
	v_fmac_f32_e32 v139, v168, v1
	v_pk_fma_f32 v[30:31], v[68:69], v[22:23], v[30:31]
	v_fmac_f32_e32 v138, v167, v1
	v_pk_fma_f32 v[236:237], v[66:67], v[22:23], v[236:237]
	v_fmac_f32_e32 v137, v166, v1
	v_pk_fma_f32 v[28:29], v[64:65], v[22:23], v[28:29]
	v_fmac_f32_e32 v136, v196, v1
	v_pk_fma_f32 v[238:239], v[62:63], v[22:23], v[238:239]
	v_fmac_f32_e32 v135, v195, v1
	v_pk_fma_f32 v[26:27], v[60:61], v[22:23], v[26:27]
	v_fmac_f32_e32 v134, v194, v1
	v_pk_fma_f32 v[240:241], v[58:59], v[22:23], v[240:241]
	v_fmac_f32_e32 v133, v193, v1
	v_pk_fma_f32 v[24:25], v[118:119], v[22:23], v[24:25]
	v_fmac_f32_e32 v5, v192, v1
	v_pk_fma_f32 v[242:243], v[116:117], v[22:23], v[242:243]
	v_fmac_f32_e32 v2, v191, v1
	v_pk_fma_f32 v[22:23], v[114:115], v[22:23], v[120:121]
	v_fma_f32 v7, v190, v1, v197
	v_lshlrev_b32_e32 v244, 16, v20
	v_and_b32_e32 v245, 0xffff0000, v20
	v_lshlrev_b32_e32 v1, 16, v224
	v_pk_fma_f32 v[38:39], v[84:85], v[244:245], v[38:39]
	v_fmac_f32_e32 v145, v175, v1
	v_pk_fma_f32 v[36:37], v[82:83], v[244:245], v[36:37]
	v_fmac_f32_e32 v144, v174, v1
	v_pk_fma_f32 v[224:225], v[80:81], v[244:245], v[230:231]
	v_fmac_f32_e32 v143, v173, v1
	v_pk_fma_f32 v[34:35], v[78:79], v[244:245], v[34:35]
	v_fmac_f32_e32 v142, v172, v1
	v_pk_fma_f32 v[230:231], v[76:77], v[244:245], v[232:233]
	v_fmac_f32_e32 v141, v171, v1
	v_pk_fma_f32 v[32:33], v[74:75], v[244:245], v[32:33]
	v_fmac_f32_e32 v140, v170, v1
	v_pk_fma_f32 v[232:233], v[72:73], v[244:245], v[234:235]
	v_fmac_f32_e32 v139, v169, v1
	v_pk_fma_f32 v[30:31], v[70:71], v[244:245], v[30:31]
	v_fmac_f32_e32 v138, v168, v1
	v_pk_fma_f32 v[234:235], v[68:69], v[244:245], v[236:237]
	v_fmac_f32_e32 v137, v167, v1
	v_pk_fma_f32 v[28:29], v[66:67], v[244:245], v[28:29]
	v_fmac_f32_e32 v136, v166, v1
	v_pk_fma_f32 v[236:237], v[64:65], v[244:245], v[238:239]
	v_fmac_f32_e32 v135, v196, v1
	v_pk_fma_f32 v[26:27], v[62:63], v[244:245], v[26:27]
	v_fmac_f32_e32 v134, v195, v1
	v_pk_fma_f32 v[238:239], v[60:61], v[244:245], v[240:241]
	v_fmac_f32_e32 v133, v194, v1
	v_pk_fma_f32 v[24:25], v[58:59], v[244:245], v[24:25]
	v_fmac_f32_e32 v5, v193, v1
	v_pk_fma_f32 v[240:241], v[118:119], v[244:245], v[242:243]
	v_fmac_f32_e32 v2, v192, v1
	v_pk_fma_f32 v[22:23], v[116:117], v[244:245], v[22:23]
	v_fmac_f32_e32 v7, v191, v1
	v_lshlrev_b32_e32 v20, 16, v21
	v_and_b32_e32 v21, 0xffff0000, v21
	v_lshlrev_b32_e32 v1, 16, v223
	v_pk_fma_f32 v[38:39], v[86:87], v[20:21], v[38:39]
	v_fmac_f32_e32 v145, v176, v1
	v_pk_fma_f32 v[36:37], v[84:85], v[20:21], v[36:37]
	v_fmac_f32_e32 v144, v175, v1
	v_pk_fma_f32 v[224:225], v[82:83], v[20:21], v[224:225]
	v_fmac_f32_e32 v143, v174, v1
	v_pk_fma_f32 v[34:35], v[80:81], v[20:21], v[34:35]
	v_fmac_f32_e32 v142, v173, v1
	v_pk_fma_f32 v[230:231], v[78:79], v[20:21], v[230:231]
	v_fmac_f32_e32 v141, v172, v1
	v_pk_fma_f32 v[32:33], v[76:77], v[20:21], v[32:33]
	v_fmac_f32_e32 v140, v171, v1
	v_pk_fma_f32 v[232:233], v[74:75], v[20:21], v[232:233]
	v_fmac_f32_e32 v139, v170, v1
	v_pk_fma_f32 v[30:31], v[72:73], v[20:21], v[30:31]
	v_fmac_f32_e32 v138, v169, v1
	v_pk_fma_f32 v[234:235], v[70:71], v[20:21], v[234:235]
	v_fmac_f32_e32 v137, v168, v1
	v_pk_fma_f32 v[28:29], v[68:69], v[20:21], v[28:29]
	v_fmac_f32_e32 v136, v167, v1
	v_pk_fma_f32 v[236:237], v[66:67], v[20:21], v[236:237]
	v_fmac_f32_e32 v135, v166, v1
	v_pk_fma_f32 v[26:27], v[64:65], v[20:21], v[26:27]
	v_fmac_f32_e32 v134, v196, v1
	v_pk_fma_f32 v[238:239], v[62:63], v[20:21], v[238:239]
	v_fmac_f32_e32 v133, v195, v1
	v_pk_fma_f32 v[24:25], v[60:61], v[20:21], v[24:25]
	v_fmac_f32_e32 v5, v194, v1
	v_pk_fma_f32 v[240:241], v[58:59], v[20:21], v[240:241]
	v_fmac_f32_e32 v2, v193, v1
	v_pk_fma_f32 v[20:21], v[118:119], v[20:21], v[22:23]
	v_fmac_f32_e32 v7, v192, v1
	v_lshlrev_b32_e32 v22, 16, v18
	v_and_b32_e32 v23, 0xffff0000, v18
	v_lshlrev_b32_e32 v1, 16, v222
	v_pk_fma_f32 v[38:39], v[88:89], v[22:23], v[38:39]
	v_fmac_f32_e32 v145, v177, v1
	v_pk_fma_f32 v[36:37], v[86:87], v[22:23], v[36:37]
	v_fmac_f32_e32 v144, v176, v1
	v_pk_fma_f32 v[222:223], v[84:85], v[22:23], v[224:225]
	v_fmac_f32_e32 v143, v175, v1
	v_pk_fma_f32 v[34:35], v[82:83], v[22:23], v[34:35]
	v_fmac_f32_e32 v142, v174, v1
; #define LAS __attribute__((address_space(3)))
; __device__ __forceinline__ float bf_lo(unsigned w) { return __uint_as_float(w << 16); }
; __device__ __forceinline__ float bf_hi(unsigned w) { return __uint_as_float(w & 0xffff0000u); }
; __device__ __forceinline__ void p2_conv_unit_prompt(Frame& F, int unit, int next_pm, const ConvW& cw, size_t src_off = WS_A, size_t dst_off = WS_CACT) {
;     ...
; #pragma unroll
;         for (int rg = 0; rg < CV_ROWS; rg += 8) {
;             unsigned w2[8], w1[8];
; #pragma unroll
;             for (int i = 0; i < 8; ++i) if (rg + i < CV_ROWS) { const LAS unsigned char* rp = S + (rg + i) * (DCONV * 2) + ((rg + i) < CW - 1 ? ringLo : ringHi);
;                 w2[i] = *(const LAS unsigned*)(rp + p * 2u); w1[i] = *(const LAS unsigned short*)(rp + q * 2u); }
; #pragma unroll
;             for (int i = 0; i < 8; ++i) if (rg + i < CV_ROWS) { const int rr = rg + i; const f32x2 vp = (f32x2){bf_lo(w2[i]), bf_hi(w2[i])}; const float vq = bf_lo(w1[i]);
; #pragma unroll
;                 for (int t = 0; t < 16; ++t) { const int j = rr - t; if (j >= 0 && j < CW) { ap[t] += wp[j] * vp; aq[t] += wq[j] * vq; } } }
;             __builtin_amdgcn_sched_barrier(0); }
	v_pk_fma_f32 v[224:225], v[80:81], v[22:23], v[230:231]
	v_fmac_f32_e32 v141, v173, v1
	v_pk_fma_f32 v[32:33], v[78:79], v[22:23], v[32:33]
	v_fmac_f32_e32 v140, v172, v1
	v_pk_fma_f32 v[230:231], v[76:77], v[22:23], v[232:233]
	v_fmac_f32_e32 v139, v171, v1
	v_pk_fma_f32 v[30:31], v[74:75], v[22:23], v[30:31]
	v_fmac_f32_e32 v138, v170, v1
	v_pk_fma_f32 v[232:233], v[72:73], v[22:23], v[234:235]
	v_fmac_f32_e32 v137, v169, v1
	v_pk_fma_f32 v[28:29], v[70:71], v[22:23], v[28:29]
	v_fmac_f32_e32 v136, v168, v1
	v_pk_fma_f32 v[234:235], v[68:69], v[22:23], v[236:237]
	v_fmac_f32_e32 v135, v167, v1
	v_pk_fma_f32 v[26:27], v[66:67], v[22:23], v[26:27]
	v_fmac_f32_e32 v134, v166, v1
	v_pk_fma_f32 v[236:237], v[64:65], v[22:23], v[238:239]
	v_fmac_f32_e32 v133, v196, v1
	v_pk_fma_f32 v[24:25], v[62:63], v[22:23], v[24:25]
	v_fmac_f32_e32 v5, v195, v1
	v_pk_fma_f32 v[238:239], v[60:61], v[22:23], v[240:241]
	v_fmac_f32_e32 v2, v194, v1
	v_pk_fma_f32 v[20:21], v[58:59], v[22:23], v[20:21]
	v_fmac_f32_e32 v7, v193, v1
	v_lshlrev_b32_e32 v18, 16, v19
	v_and_b32_e32 v19, 0xffff0000, v19
	v_lshlrev_b32_e32 v1, 16, v221
	v_pk_fma_f32 v[22:23], v[90:91], v[18:19], v[38:39]
	v_fmac_f32_e32 v145, v178, v1
	v_pk_fma_f32 v[36:37], v[88:89], v[18:19], v[36:37]
	v_fmac_f32_e32 v144, v177, v1
	v_pk_fma_f32 v[38:39], v[86:87], v[18:19], v[222:223]
	v_fmac_f32_e32 v143, v176, v1
	v_pk_fma_f32 v[34:35], v[84:85], v[18:19], v[34:35]
	v_fmac_f32_e32 v142, v175, v1
	v_pk_fma_f32 v[222:223], v[82:83], v[18:19], v[224:225]
	v_fmac_f32_e32 v141, v174, v1
	v_pk_fma_f32 v[32:33], v[80:81], v[18:19], v[32:33]
	v_fmac_f32_e32 v140, v173, v1
	v_pk_fma_f32 v[224:225], v[78:79], v[18:19], v[230:231]
	v_fmac_f32_e32 v139, v172, v1
	v_pk_fma_f32 v[30:31], v[76:77], v[18:19], v[30:31]
	v_fmac_f32_e32 v138, v171, v1
	v_pk_fma_f32 v[230:231], v[74:75], v[18:19], v[232:233]
	v_fmac_f32_e32 v137, v170, v1
	v_pk_fma_f32 v[28:29], v[72:73], v[18:19], v[28:29]
	v_fmac_f32_e32 v136, v169, v1
	v_pk_fma_f32 v[232:233], v[70:71], v[18:19], v[234:235]
	v_fmac_f32_e32 v135, v168, v1
	v_pk_fma_f32 v[26:27], v[68:69], v[18:19], v[26:27]
	v_fmac_f32_e32 v134, v167, v1
	v_pk_fma_f32 v[234:235], v[66:67], v[18:19], v[236:237]
	v_fmac_f32_e32 v133, v166, v1
	v_pk_fma_f32 v[24:25], v[64:65], v[18:19], v[24:25]
	v_fmac_f32_e32 v5, v196, v1
	v_pk_fma_f32 v[236:237], v[62:63], v[18:19], v[238:239]
	v_fmac_f32_e32 v2, v195, v1
	v_pk_fma_f32 v[18:19], v[60:61], v[18:19], v[20:21]
	v_fmac_f32_e32 v7, v194, v1
	v_lshlrev_b32_e32 v20, 16, v16
	v_and_b32_e32 v21, 0xffff0000, v16
	v_lshlrev_b32_e32 v1, 16, v220
	v_pk_fma_f32 v[22:23], v[92:93], v[20:21], v[22:23]
	v_fmac_f32_e32 v145, v179, v1
	v_pk_fma_f32 v[36:37], v[90:91], v[20:21], v[36:37]
	v_fmac_f32_e32 v144, v178, v1
	v_pk_fma_f32 v[38:39], v[88:89], v[20:21], v[38:39]
	v_fmac_f32_e32 v143, v177, v1
	v_pk_fma_f32 v[34:35], v[86:87], v[20:21], v[34:35]
	v_fmac_f32_e32 v142, v176, v1
	v_pk_fma_f32 v[220:221], v[84:85], v[20:21], v[222:223]
	v_fmac_f32_e32 v141, v175, v1
	v_pk_fma_f32 v[32:33], v[82:83], v[20:21], v[32:33]
	v_fmac_f32_e32 v140, v174, v1
	v_pk_fma_f32 v[222:223], v[80:81], v[20:21], v[224:225]
	v_fmac_f32_e32 v139, v173, v1
	v_pk_fma_f32 v[30:31], v[78:79], v[20:21], v[30:31]
	v_fmac_f32_e32 v138, v172, v1
	v_pk_fma_f32 v[224:225], v[76:77], v[20:21], v[230:231]
	v_fmac_f32_e32 v137, v171, v1
	v_pk_fma_f32 v[28:29], v[74:75], v[20:21], v[28:29]
	v_fmac_f32_e32 v136, v170, v1
	v_pk_fma_f32 v[230:231], v[72:73], v[20:21], v[232:233]
	v_fmac_f32_e32 v135, v169, v1
	v_pk_fma_f32 v[26:27], v[70:71], v[20:21], v[26:27]
	v_fmac_f32_e32 v134, v168, v1
	v_pk_fma_f32 v[232:233], v[68:69], v[20:21], v[234:235]
	v_fmac_f32_e32 v133, v167, v1
	v_pk_fma_f32 v[24:25], v[66:67], v[20:21], v[24:25]
	v_fmac_f32_e32 v5, v166, v1
	v_pk_fma_f32 v[234:235], v[64:65], v[20:21], v[236:237]
	v_fmac_f32_e32 v2, v196, v1
	v_pk_fma_f32 v[18:19], v[62:63], v[20:21], v[18:19]
	v_fmac_f32_e32 v7, v195, v1
	v_lshlrev_b32_e32 v16, 16, v17
	v_and_b32_e32 v17, 0xffff0000, v17
	v_lshlrev_b32_e32 v1, 16, v219
	v_pk_fma_f32 v[20:21], v[94:95], v[16:17], v[22:23]
	v_fmac_f32_e32 v145, v180, v1
	v_pk_fma_f32 v[22:23], v[92:93], v[16:17], v[36:37]
	v_fmac_f32_e32 v144, v179, v1
	v_pk_fma_f32 v[36:37], v[90:91], v[16:17], v[38:39]
	v_fmac_f32_e32 v143, v178, v1
	v_pk_fma_f32 v[34:35], v[88:89], v[16:17], v[34:35]
	v_fmac_f32_e32 v142, v177, v1
	v_pk_fma_f32 v[38:39], v[86:87], v[16:17], v[220:221]
	v_fmac_f32_e32 v141, v176, v1
	v_pk_fma_f32 v[32:33], v[84:85], v[16:17], v[32:33]
	v_fmac_f32_e32 v140, v175, v1
	v_pk_fma_f32 v[220:221], v[82:83], v[16:17], v[222:223]
	v_fmac_f32_e32 v139, v174, v1
	v_pk_fma_f32 v[30:31], v[80:81], v[16:17], v[30:31]
	v_fmac_f32_e32 v138, v173, v1
	v_pk_fma_f32 v[222:223], v[78:79], v[16:17], v[224:225]
	v_fmac_f32_e32 v137, v172, v1
	v_pk_fma_f32 v[28:29], v[76:77], v[16:17], v[28:29]
	v_fmac_f32_e32 v136, v171, v1
	v_pk_fma_f32 v[224:225], v[74:75], v[16:17], v[230:231]
	v_fmac_f32_e32 v135, v170, v1
	v_pk_fma_f32 v[26:27], v[72:73], v[16:17], v[26:27]
	v_fmac_f32_e32 v134, v169, v1
	v_pk_fma_f32 v[230:231], v[70:71], v[16:17], v[232:233]
	v_fmac_f32_e32 v133, v168, v1
	v_pk_fma_f32 v[24:25], v[68:69], v[16:17], v[24:25]
	v_fmac_f32_e32 v5, v167, v1
	v_pk_fma_f32 v[232:233], v[66:67], v[16:17], v[234:235]
	v_fmac_f32_e32 v2, v166, v1
	v_pk_fma_f32 v[16:17], v[64:65], v[16:17], v[18:19]
	v_fmac_f32_e32 v7, v196, v1
	v_lshlrev_b32_e32 v18, 16, v218
	v_and_b32_e32 v19, 0xffff0000, v218
	v_lshlrev_b32_e32 v1, 16, v217
	v_pk_fma_f32 v[20:21], v[96:97], v[18:19], v[20:21]
	v_fmac_f32_e32 v145, v181, v1
	v_pk_fma_f32 v[22:23], v[94:95], v[18:19], v[22:23]
; #define LAS __attribute__((address_space(3)))
; __device__ __forceinline__ float bf_lo(unsigned w) { return __uint_as_float(w << 16); }
; __device__ __forceinline__ float bf_hi(unsigned w) { return __uint_as_float(w & 0xffff0000u); }
; __device__ __forceinline__ void p2_conv_unit_prompt(Frame& F, int unit, int next_pm, const ConvW& cw, size_t src_off = WS_A, size_t dst_off = WS_CACT) {
;     ...
; #pragma unroll
;         for (int rg = 0; rg < CV_ROWS; rg += 8) {
;             unsigned w2[8], w1[8];
; #pragma unroll
;             for (int i = 0; i < 8; ++i) if (rg + i < CV_ROWS) { const LAS unsigned char* rp = S + (rg + i) * (DCONV * 2) + ((rg + i) < CW - 1 ? ringLo : ringHi);
;                 w2[i] = *(const LAS unsigned*)(rp + p * 2u); w1[i] = *(const LAS unsigned short*)(rp + q * 2u); }
; #pragma unroll
;             for (int i = 0; i < 8; ++i) if (rg + i < CV_ROWS) { const int rr = rg + i; const f32x2 vp = (f32x2){bf_lo(w2[i]), bf_hi(w2[i])}; const float vq = bf_lo(w1[i]);
; #pragma unroll
;                 for (int t = 0; t < 16; ++t) { const int j = rr - t; if (j >= 0 && j < CW) { ap[t] += wp[j] * vp; aq[t] += wq[j] * vq; } } }
;             __builtin_amdgcn_sched_barrier(0); }
	v_fmac_f32_e32 v144, v180, v1
	v_pk_fma_f32 v[36:37], v[92:93], v[18:19], v[36:37]
	v_fmac_f32_e32 v143, v179, v1
	v_pk_fma_f32 v[34:35], v[90:91], v[18:19], v[34:35]
	v_fmac_f32_e32 v142, v178, v1
	v_pk_fma_f32 v[38:39], v[88:89], v[18:19], v[38:39]
	v_fmac_f32_e32 v141, v177, v1
	v_pk_fma_f32 v[32:33], v[86:87], v[18:19], v[32:33]
	v_fmac_f32_e32 v140, v176, v1
	v_pk_fma_f32 v[218:219], v[84:85], v[18:19], v[220:221]
	v_fmac_f32_e32 v139, v175, v1
	v_pk_fma_f32 v[30:31], v[82:83], v[18:19], v[30:31]
	v_fmac_f32_e32 v138, v174, v1
	v_pk_fma_f32 v[220:221], v[80:81], v[18:19], v[222:223]
	v_fmac_f32_e32 v137, v173, v1
	v_pk_fma_f32 v[28:29], v[78:79], v[18:19], v[28:29]
	v_fmac_f32_e32 v136, v172, v1
	v_pk_fma_f32 v[222:223], v[76:77], v[18:19], v[224:225]
	v_fmac_f32_e32 v135, v171, v1
	v_pk_fma_f32 v[26:27], v[74:75], v[18:19], v[26:27]
	v_fmac_f32_e32 v134, v170, v1
	v_pk_fma_f32 v[224:225], v[72:73], v[18:19], v[230:231]
	v_fmac_f32_e32 v133, v169, v1
	v_pk_fma_f32 v[24:25], v[70:71], v[18:19], v[24:25]
	v_fmac_f32_e32 v5, v168, v1
	v_pk_fma_f32 v[230:231], v[68:69], v[18:19], v[232:233]
	v_fmac_f32_e32 v2, v167, v1
	v_pk_fma_f32 v[16:17], v[66:67], v[18:19], v[16:17]
	v_fmac_f32_e32 v7, v166, v1
	v_lshlrev_b32_e32 v18, 16, v216
	v_and_b32_e32 v19, 0xffff0000, v216
	v_lshlrev_b32_e32 v1, 16, v215
	v_pk_fma_f32 v[20:21], v[98:99], v[18:19], v[20:21]
	v_fmac_f32_e32 v145, v182, v1
	v_pk_fma_f32 v[22:23], v[96:97], v[18:19], v[22:23]
	v_fmac_f32_e32 v144, v181, v1
	v_pk_fma_f32 v[36:37], v[94:95], v[18:19], v[36:37]
	v_fmac_f32_e32 v143, v180, v1
	v_pk_fma_f32 v[34:35], v[92:93], v[18:19], v[34:35]
	v_fmac_f32_e32 v142, v179, v1
	v_pk_fma_f32 v[38:39], v[90:91], v[18:19], v[38:39]
	v_fmac_f32_e32 v141, v178, v1
	v_pk_fma_f32 v[32:33], v[88:89], v[18:19], v[32:33]
	v_fmac_f32_e32 v140, v177, v1
	v_pk_fma_f32 v[214:215], v[86:87], v[18:19], v[218:219]
	v_fmac_f32_e32 v139, v176, v1
	v_pk_fma_f32 v[30:31], v[84:85], v[18:19], v[30:31]
	v_fmac_f32_e32 v138, v175, v1
	v_pk_fma_f32 v[216:217], v[82:83], v[18:19], v[220:221]
	v_fmac_f32_e32 v137, v174, v1
	v_pk_fma_f32 v[28:29], v[80:81], v[18:19], v[28:29]
	v_fmac_f32_e32 v136, v173, v1
	v_pk_fma_f32 v[218:219], v[78:79], v[18:19], v[222:223]
	v_fmac_f32_e32 v135, v172, v1
	v_pk_fma_f32 v[26:27], v[76:77], v[18:19], v[26:27]
	v_fmac_f32_e32 v134, v171, v1
	v_pk_fma_f32 v[220:221], v[74:75], v[18:19], v[224:225]
	v_fmac_f32_e32 v133, v170, v1
	v_pk_fma_f32 v[24:25], v[72:73], v[18:19], v[24:25]
	v_fmac_f32_e32 v5, v169, v1
	v_pk_fma_f32 v[222:223], v[70:71], v[18:19], v[230:231]
	v_fmac_f32_e32 v2, v168, v1
	v_pk_fma_f32 v[16:17], v[68:69], v[18:19], v[16:17]
	v_fmac_f32_e32 v7, v167, v1
	v_lshlrev_b32_e32 v18, 16, v213
	v_and_b32_e32 v19, 0xffff0000, v213
	v_lshlrev_b32_e32 v1, 16, v212
	v_pk_fma_f32 v[20:21], v[100:101], v[18:19], v[20:21]
	v_fmac_f32_e32 v145, v183, v1
	v_pk_fma_f32 v[22:23], v[98:99], v[18:19], v[22:23]
	v_fmac_f32_e32 v144, v182, v1
	v_pk_fma_f32 v[36:37], v[96:97], v[18:19], v[36:37]
	v_fmac_f32_e32 v143, v181, v1
	v_pk_fma_f32 v[34:35], v[94:95], v[18:19], v[34:35]
	v_fmac_f32_e32 v142, v180, v1
	v_pk_fma_f32 v[38:39], v[92:93], v[18:19], v[38:39]
	v_fmac_f32_e32 v141, v179, v1
	v_pk_fma_f32 v[32:33], v[90:91], v[18:19], v[32:33]
	v_fmac_f32_e32 v140, v178, v1
	v_pk_fma_f32 v[212:213], v[88:89], v[18:19], v[214:215]
	v_fmac_f32_e32 v139, v177, v1
	v_pk_fma_f32 v[30:31], v[86:87], v[18:19], v[30:31]
	v_fmac_f32_e32 v138, v176, v1
	v_pk_fma_f32 v[214:215], v[84:85], v[18:19], v[216:217]
	v_fmac_f32_e32 v137, v175, v1
	v_pk_fma_f32 v[28:29], v[82:83], v[18:19], v[28:29]
	v_fmac_f32_e32 v136, v174, v1
	v_pk_fma_f32 v[216:217], v[80:81], v[18:19], v[218:219]
	v_fmac_f32_e32 v135, v173, v1
	v_pk_fma_f32 v[26:27], v[78:79], v[18:19], v[26:27]
	v_fmac_f32_e32 v134, v172, v1
	v_pk_fma_f32 v[218:219], v[76:77], v[18:19], v[220:221]
	v_fmac_f32_e32 v133, v171, v1
	v_pk_fma_f32 v[24:25], v[74:75], v[18:19], v[24:25]
	v_fmac_f32_e32 v5, v170, v1
	v_pk_fma_f32 v[220:221], v[72:73], v[18:19], v[222:223]
	v_fmac_f32_e32 v2, v169, v1
	v_pk_fma_f32 v[16:17], v[70:71], v[18:19], v[16:17]
	v_fmac_f32_e32 v7, v168, v1
	v_lshlrev_b32_e32 v18, 16, v211
	v_and_b32_e32 v19, 0xffff0000, v211
	v_lshlrev_b32_e32 v1, 16, v210
	v_pk_fma_f32 v[20:21], v[102:103], v[18:19], v[20:21]
	v_fmac_f32_e32 v145, v184, v1
	v_pk_fma_f32 v[22:23], v[100:101], v[18:19], v[22:23]
	v_fmac_f32_e32 v144, v183, v1
	v_pk_fma_f32 v[36:37], v[98:99], v[18:19], v[36:37]
	v_fmac_f32_e32 v143, v182, v1
	v_pk_fma_f32 v[34:35], v[96:97], v[18:19], v[34:35]
	v_fmac_f32_e32 v142, v181, v1
	v_pk_fma_f32 v[38:39], v[94:95], v[18:19], v[38:39]
	v_fmac_f32_e32 v141, v180, v1
	v_pk_fma_f32 v[32:33], v[92:93], v[18:19], v[32:33]
	v_fmac_f32_e32 v140, v179, v1
	v_pk_fma_f32 v[210:211], v[90:91], v[18:19], v[212:213]
	v_fmac_f32_e32 v139, v178, v1
	v_pk_fma_f32 v[30:31], v[88:89], v[18:19], v[30:31]
	v_fmac_f32_e32 v138, v177, v1
	v_pk_fma_f32 v[212:213], v[86:87], v[18:19], v[214:215]
	v_fmac_f32_e32 v137, v176, v1
	v_pk_fma_f32 v[28:29], v[84:85], v[18:19], v[28:29]
	v_fmac_f32_e32 v136, v175, v1
	v_pk_fma_f32 v[214:215], v[82:83], v[18:19], v[216:217]
	v_fmac_f32_e32 v135, v174, v1
	v_pk_fma_f32 v[26:27], v[80:81], v[18:19], v[26:27]
	v_fmac_f32_e32 v134, v173, v1
	v_pk_fma_f32 v[216:217], v[78:79], v[18:19], v[218:219]
	v_fmac_f32_e32 v133, v172, v1
	v_pk_fma_f32 v[24:25], v[76:77], v[18:19], v[24:25]
	v_fmac_f32_e32 v5, v171, v1
	v_pk_fma_f32 v[218:219], v[74:75], v[18:19], v[220:221]
	v_fmac_f32_e32 v2, v170, v1
	v_pk_fma_f32 v[16:17], v[72:73], v[18:19], v[16:17]
	v_fmac_f32_e32 v7, v169, v1
	v_lshlrev_b32_e32 v18, 16, v209
; #define LAS __attribute__((address_space(3)))
; __device__ __forceinline__ float bf_lo(unsigned w) { return __uint_as_float(w << 16); }
; __device__ __forceinline__ float bf_hi(unsigned w) { return __uint_as_float(w & 0xffff0000u); }
; __device__ __forceinline__ void p2_conv_unit_prompt(Frame& F, int unit, int next_pm, const ConvW& cw, size_t src_off = WS_A, size_t dst_off = WS_CACT) {
;     ...
; #pragma unroll
;         for (int rg = 0; rg < CV_ROWS; rg += 8) {
;             unsigned w2[8], w1[8];
; #pragma unroll
;             for (int i = 0; i < 8; ++i) if (rg + i < CV_ROWS) { const LAS unsigned char* rp = S + (rg + i) * (DCONV * 2) + ((rg + i) < CW - 1 ? ringLo : ringHi);
;                 w2[i] = *(const LAS unsigned*)(rp + p * 2u); w1[i] = *(const LAS unsigned short*)(rp + q * 2u); }
; #pragma unroll
;             for (int i = 0; i < 8; ++i) if (rg + i < CV_ROWS) { const int rr = rg + i; const f32x2 vp = (f32x2){bf_lo(w2[i]), bf_hi(w2[i])}; const float vq = bf_lo(w1[i]);
; #pragma unroll
;                 for (int t = 0; t < 16; ++t) { const int j = rr - t; if (j >= 0 && j < CW) { ap[t] += wp[j] * vp; aq[t] += wq[j] * vq; } } }
;             __builtin_amdgcn_sched_barrier(0); }
	v_and_b32_e32 v19, 0xffff0000, v209
	v_lshlrev_b32_e32 v1, 16, v208
	v_pk_fma_f32 v[20:21], v[104:105], v[18:19], v[20:21]
	v_fmac_f32_e32 v145, v185, v1
	v_pk_fma_f32 v[22:23], v[102:103], v[18:19], v[22:23]
	v_fmac_f32_e32 v144, v184, v1
	v_pk_fma_f32 v[36:37], v[100:101], v[18:19], v[36:37]
	v_fmac_f32_e32 v143, v183, v1
	v_pk_fma_f32 v[34:35], v[98:99], v[18:19], v[34:35]
	v_fmac_f32_e32 v142, v182, v1
	v_pk_fma_f32 v[38:39], v[96:97], v[18:19], v[38:39]
	v_fmac_f32_e32 v141, v181, v1
	v_pk_fma_f32 v[32:33], v[94:95], v[18:19], v[32:33]
	v_fmac_f32_e32 v140, v180, v1
	v_pk_fma_f32 v[208:209], v[92:93], v[18:19], v[210:211]
	v_fmac_f32_e32 v139, v179, v1
	v_pk_fma_f32 v[30:31], v[90:91], v[18:19], v[30:31]
	v_fmac_f32_e32 v138, v178, v1
	v_pk_fma_f32 v[210:211], v[88:89], v[18:19], v[212:213]
	v_fmac_f32_e32 v137, v177, v1
	v_pk_fma_f32 v[28:29], v[86:87], v[18:19], v[28:29]
	v_fmac_f32_e32 v136, v176, v1
	v_pk_fma_f32 v[212:213], v[84:85], v[18:19], v[214:215]
	v_fmac_f32_e32 v135, v175, v1
	v_pk_fma_f32 v[26:27], v[82:83], v[18:19], v[26:27]
	v_fmac_f32_e32 v134, v174, v1
	v_pk_fma_f32 v[214:215], v[80:81], v[18:19], v[216:217]
	v_fmac_f32_e32 v133, v173, v1
	v_pk_fma_f32 v[24:25], v[78:79], v[18:19], v[24:25]
	v_fmac_f32_e32 v5, v172, v1
	v_pk_fma_f32 v[216:217], v[76:77], v[18:19], v[218:219]
	v_fmac_f32_e32 v2, v171, v1
	v_pk_fma_f32 v[16:17], v[74:75], v[18:19], v[16:17]
	v_fmac_f32_e32 v7, v170, v1
	v_lshlrev_b32_e32 v18, 16, v207
	v_and_b32_e32 v19, 0xffff0000, v207
	v_lshlrev_b32_e32 v1, 16, v206
	v_pk_fma_f32 v[20:21], v[106:107], v[18:19], v[20:21]
	v_fmac_f32_e32 v145, v186, v1
	v_pk_fma_f32 v[22:23], v[104:105], v[18:19], v[22:23]
	v_fmac_f32_e32 v144, v185, v1
	v_pk_fma_f32 v[36:37], v[102:103], v[18:19], v[36:37]
	v_fmac_f32_e32 v143, v184, v1
	v_pk_fma_f32 v[34:35], v[100:101], v[18:19], v[34:35]
	v_fmac_f32_e32 v142, v183, v1
	v_pk_fma_f32 v[38:39], v[98:99], v[18:19], v[38:39]
	v_fmac_f32_e32 v141, v182, v1
	v_pk_fma_f32 v[32:33], v[96:97], v[18:19], v[32:33]
	v_fmac_f32_e32 v140, v181, v1
	v_pk_fma_f32 v[206:207], v[94:95], v[18:19], v[208:209]
	v_fmac_f32_e32 v139, v180, v1
	v_pk_fma_f32 v[30:31], v[92:93], v[18:19], v[30:31]
	v_fmac_f32_e32 v138, v179, v1
	v_pk_fma_f32 v[208:209], v[90:91], v[18:19], v[210:211]
	v_fmac_f32_e32 v137, v178, v1
	v_pk_fma_f32 v[28:29], v[88:89], v[18:19], v[28:29]
	v_fmac_f32_e32 v136, v177, v1
	v_pk_fma_f32 v[210:211], v[86:87], v[18:19], v[212:213]
	v_fmac_f32_e32 v135, v176, v1
	v_pk_fma_f32 v[26:27], v[84:85], v[18:19], v[26:27]
	v_fmac_f32_e32 v134, v175, v1
	v_pk_fma_f32 v[212:213], v[82:83], v[18:19], v[214:215]
	v_fmac_f32_e32 v133, v174, v1
	v_pk_fma_f32 v[24:25], v[80:81], v[18:19], v[24:25]
	v_fmac_f32_e32 v5, v173, v1
	v_pk_fma_f32 v[214:215], v[78:79], v[18:19], v[216:217]
	v_fmac_f32_e32 v2, v172, v1
	v_pk_fma_f32 v[16:17], v[76:77], v[18:19], v[16:17]
	v_fmac_f32_e32 v7, v171, v1
	v_lshlrev_b32_e32 v18, 16, v205
	v_and_b32_e32 v19, 0xffff0000, v205
	v_lshlrev_b32_e32 v1, 16, v204
	v_pk_fma_f32 v[20:21], v[108:109], v[18:19], v[20:21]
	v_fmac_f32_e32 v145, v187, v1
	v_pk_fma_f32 v[22:23], v[106:107], v[18:19], v[22:23]
	v_fmac_f32_e32 v144, v186, v1
	v_pk_fma_f32 v[36:37], v[104:105], v[18:19], v[36:37]
	v_fmac_f32_e32 v143, v185, v1
	v_pk_fma_f32 v[34:35], v[102:103], v[18:19], v[34:35]
	v_fmac_f32_e32 v142, v184, v1
	v_pk_fma_f32 v[38:39], v[100:101], v[18:19], v[38:39]
	v_fmac_f32_e32 v141, v183, v1
	v_pk_fma_f32 v[32:33], v[98:99], v[18:19], v[32:33]
	v_fmac_f32_e32 v140, v182, v1
	v_pk_fma_f32 v[204:205], v[96:97], v[18:19], v[206:207]
	v_fmac_f32_e32 v139, v181, v1
	v_pk_fma_f32 v[30:31], v[94:95], v[18:19], v[30:31]
	v_fmac_f32_e32 v138, v180, v1
	v_pk_fma_f32 v[206:207], v[92:93], v[18:19], v[208:209]
	v_fmac_f32_e32 v137, v179, v1
	v_pk_fma_f32 v[28:29], v[90:91], v[18:19], v[28:29]
	v_fmac_f32_e32 v136, v178, v1
	v_pk_fma_f32 v[208:209], v[88:89], v[18:19], v[210:211]
	v_fmac_f32_e32 v135, v177, v1
	v_pk_fma_f32 v[26:27], v[86:87], v[18:19], v[26:27]
	v_fmac_f32_e32 v134, v176, v1
	v_pk_fma_f32 v[210:211], v[84:85], v[18:19], v[212:213]
	v_fmac_f32_e32 v133, v175, v1
	v_pk_fma_f32 v[24:25], v[82:83], v[18:19], v[24:25]
	v_fmac_f32_e32 v5, v174, v1
	v_pk_fma_f32 v[212:213], v[80:81], v[18:19], v[214:215]
	v_fmac_f32_e32 v2, v173, v1
	v_pk_fma_f32 v[16:17], v[78:79], v[18:19], v[16:17]
	v_fmac_f32_e32 v7, v172, v1
	v_lshlrev_b32_e32 v18, 16, v203
	v_and_b32_e32 v19, 0xffff0000, v203
	v_lshlrev_b32_e32 v1, 16, v202
	v_pk_fma_f32 v[20:21], v[110:111], v[18:19], v[20:21]
	v_fmac_f32_e32 v145, v188, v1
	v_pk_fma_f32 v[22:23], v[108:109], v[18:19], v[22:23]
	v_fmac_f32_e32 v144, v187, v1
	v_pk_fma_f32 v[36:37], v[106:107], v[18:19], v[36:37]
	v_fmac_f32_e32 v143, v186, v1
	v_pk_fma_f32 v[34:35], v[104:105], v[18:19], v[34:35]
	v_fmac_f32_e32 v142, v185, v1
	v_pk_fma_f32 v[38:39], v[102:103], v[18:19], v[38:39]
	v_fmac_f32_e32 v141, v184, v1
	v_pk_fma_f32 v[32:33], v[100:101], v[18:19], v[32:33]
	v_fmac_f32_e32 v140, v183, v1
	v_pk_fma_f32 v[202:203], v[98:99], v[18:19], v[204:205]
	v_fmac_f32_e32 v139, v182, v1
	v_pk_fma_f32 v[30:31], v[96:97], v[18:19], v[30:31]
	v_fmac_f32_e32 v138, v181, v1
	v_pk_fma_f32 v[204:205], v[94:95], v[18:19], v[206:207]
	v_fmac_f32_e32 v137, v180, v1
	v_pk_fma_f32 v[28:29], v[92:93], v[18:19], v[28:29]
	v_fmac_f32_e32 v136, v179, v1
	v_pk_fma_f32 v[206:207], v[90:91], v[18:19], v[208:209]
	v_fmac_f32_e32 v135, v178, v1
	v_pk_fma_f32 v[26:27], v[88:89], v[18:19], v[26:27]
	v_fmac_f32_e32 v134, v177, v1
	v_pk_fma_f32 v[208:209], v[86:87], v[18:19], v[210:211]
	v_fmac_f32_e32 v133, v176, v1
	v_pk_fma_f32 v[24:25], v[84:85], v[18:19], v[24:25]
; #define LAS __attribute__((address_space(3)))
; __device__ __forceinline__ float bf_lo(unsigned w) { return __uint_as_float(w << 16); }
; __device__ __forceinline__ float bf_hi(unsigned w) { return __uint_as_float(w & 0xffff0000u); }
; __device__ __forceinline__ void p2_conv_unit_prompt(Frame& F, int unit, int next_pm, const ConvW& cw, size_t src_off = WS_A, size_t dst_off = WS_CACT) {
;     ...
; #pragma unroll
;         for (int rg = 0; rg < CV_ROWS; rg += 8) {
;             unsigned w2[8], w1[8];
; #pragma unroll
;             for (int i = 0; i < 8; ++i) if (rg + i < CV_ROWS) { const LAS unsigned char* rp = S + (rg + i) * (DCONV * 2) + ((rg + i) < CW - 1 ? ringLo : ringHi);
;                 w2[i] = *(const LAS unsigned*)(rp + p * 2u); w1[i] = *(const LAS unsigned short*)(rp + q * 2u); }
; #pragma unroll
;             for (int i = 0; i < 8; ++i) if (rg + i < CV_ROWS) { const int rr = rg + i; const f32x2 vp = (f32x2){bf_lo(w2[i]), bf_hi(w2[i])}; const float vq = bf_lo(w1[i]);
; #pragma unroll
;                 for (int t = 0; t < 16; ++t) { const int j = rr - t; if (j >= 0 && j < CW) { ap[t] += wp[j] * vp; aq[t] += wq[j] * vq; } } }
;             __builtin_amdgcn_sched_barrier(0); }
	v_fmac_f32_e32 v5, v175, v1
	v_pk_fma_f32 v[210:211], v[82:83], v[18:19], v[212:213]
	v_fmac_f32_e32 v2, v174, v1
	v_pk_fma_f32 v[16:17], v[80:81], v[18:19], v[16:17]
	v_fmac_f32_e32 v7, v173, v1
	v_lshlrev_b32_e32 v18, 16, v41
	v_and_b32_e32 v19, 0xffff0000, v41
	v_lshlrev_b32_e32 v1, 16, v40
	v_pk_fma_f32 v[40:41], v[112:113], v[18:19], v[20:21]
	v_fmac_f32_e32 v145, v189, v1
	v_pk_fma_f32 v[20:21], v[110:111], v[18:19], v[22:23]
	v_fmac_f32_e32 v144, v188, v1
	v_pk_fma_f32 v[22:23], v[108:109], v[18:19], v[36:37]
	v_fmac_f32_e32 v143, v187, v1
	v_pk_fma_f32 v[34:35], v[106:107], v[18:19], v[34:35]
	v_fmac_f32_e32 v142, v186, v1
	v_pk_fma_f32 v[36:37], v[104:105], v[18:19], v[38:39]
	v_fmac_f32_e32 v141, v185, v1
	v_pk_fma_f32 v[32:33], v[102:103], v[18:19], v[32:33]
	v_fmac_f32_e32 v140, v184, v1
	v_pk_fma_f32 v[38:39], v[100:101], v[18:19], v[202:203]
	v_fmac_f32_e32 v139, v183, v1
	v_pk_fma_f32 v[30:31], v[98:99], v[18:19], v[30:31]
	v_fmac_f32_e32 v138, v182, v1
	v_pk_fma_f32 v[202:203], v[96:97], v[18:19], v[204:205]
	v_fmac_f32_e32 v137, v181, v1
	v_pk_fma_f32 v[28:29], v[94:95], v[18:19], v[28:29]
	v_fmac_f32_e32 v136, v180, v1
	v_pk_fma_f32 v[204:205], v[92:93], v[18:19], v[206:207]
	v_fmac_f32_e32 v135, v179, v1
	v_pk_fma_f32 v[26:27], v[90:91], v[18:19], v[26:27]
	v_fmac_f32_e32 v134, v178, v1
	v_pk_fma_f32 v[206:207], v[88:89], v[18:19], v[208:209]
	v_fmac_f32_e32 v133, v177, v1
	v_pk_fma_f32 v[24:25], v[86:87], v[18:19], v[24:25]
	v_fmac_f32_e32 v5, v176, v1
	v_pk_fma_f32 v[208:209], v[84:85], v[18:19], v[210:211]
	v_fmac_f32_e32 v2, v175, v1
	v_pk_fma_f32 v[16:17], v[82:83], v[18:19], v[16:17]
	v_fmac_f32_e32 v7, v174, v1
	v_lshlrev_b32_e32 v18, 16, v47
	v_and_b32_e32 v19, 0xffff0000, v47
	v_lshlrev_b32_e32 v1, 16, v46
	v_pk_fma_f32 v[46:47], v[112:113], v[18:19], v[20:21]
	v_fmac_f32_e32 v144, v189, v1
	v_pk_fma_f32 v[20:21], v[110:111], v[18:19], v[22:23]
	v_fmac_f32_e32 v143, v188, v1
	v_pk_fma_f32 v[22:23], v[108:109], v[18:19], v[34:35]
	v_fmac_f32_e32 v142, v187, v1
	v_pk_fma_f32 v[34:35], v[106:107], v[18:19], v[36:37]
	v_fmac_f32_e32 v141, v186, v1
	v_pk_fma_f32 v[32:33], v[104:105], v[18:19], v[32:33]
	v_fmac_f32_e32 v140, v185, v1
	v_pk_fma_f32 v[36:37], v[102:103], v[18:19], v[38:39]
	v_fmac_f32_e32 v139, v184, v1
	v_pk_fma_f32 v[30:31], v[100:101], v[18:19], v[30:31]
	v_fmac_f32_e32 v138, v183, v1
	v_pk_fma_f32 v[38:39], v[98:99], v[18:19], v[202:203]
	v_fmac_f32_e32 v137, v182, v1
	v_pk_fma_f32 v[28:29], v[96:97], v[18:19], v[28:29]
	v_fmac_f32_e32 v136, v181, v1
	v_pk_fma_f32 v[202:203], v[94:95], v[18:19], v[204:205]
	v_fmac_f32_e32 v135, v180, v1
	v_pk_fma_f32 v[26:27], v[92:93], v[18:19], v[26:27]
	v_fmac_f32_e32 v134, v179, v1
	v_pk_fma_f32 v[204:205], v[90:91], v[18:19], v[206:207]
	v_fmac_f32_e32 v133, v178, v1
	v_pk_fma_f32 v[24:25], v[88:89], v[18:19], v[24:25]
	v_fmac_f32_e32 v5, v177, v1
	v_pk_fma_f32 v[206:207], v[86:87], v[18:19], v[208:209]
	v_fmac_f32_e32 v2, v176, v1
	v_pk_fma_f32 v[16:17], v[84:85], v[18:19], v[16:17]
	v_fmac_f32_e32 v7, v175, v1
	v_lshlrev_b32_e32 v18, 16, v45
	v_and_b32_e32 v19, 0xffff0000, v45
	v_lshlrev_b32_e32 v1, 16, v44
	v_pk_fma_f32 v[44:45], v[112:113], v[18:19], v[20:21]
	v_fmac_f32_e32 v143, v189, v1
	v_pk_fma_f32 v[20:21], v[110:111], v[18:19], v[22:23]
	v_fmac_f32_e32 v142, v188, v1
	v_pk_fma_f32 v[22:23], v[108:109], v[18:19], v[34:35]
	v_fmac_f32_e32 v141, v187, v1
	v_pk_fma_f32 v[32:33], v[106:107], v[18:19], v[32:33]
	v_fmac_f32_e32 v140, v186, v1
	v_pk_fma_f32 v[34:35], v[104:105], v[18:19], v[36:37]
	v_fmac_f32_e32 v139, v185, v1
	v_pk_fma_f32 v[30:31], v[102:103], v[18:19], v[30:31]
	v_fmac_f32_e32 v138, v184, v1
	v_pk_fma_f32 v[36:37], v[100:101], v[18:19], v[38:39]
	v_fmac_f32_e32 v137, v183, v1
	v_pk_fma_f32 v[28:29], v[98:99], v[18:19], v[28:29]
	v_fmac_f32_e32 v136, v182, v1
	v_pk_fma_f32 v[38:39], v[96:97], v[18:19], v[202:203]
	v_fmac_f32_e32 v135, v181, v1
	v_pk_fma_f32 v[26:27], v[94:95], v[18:19], v[26:27]
	v_fmac_f32_e32 v134, v180, v1
	v_pk_fma_f32 v[202:203], v[92:93], v[18:19], v[204:205]
	v_fmac_f32_e32 v133, v179, v1
	v_pk_fma_f32 v[24:25], v[90:91], v[18:19], v[24:25]
	v_fmac_f32_e32 v5, v178, v1
	v_pk_fma_f32 v[204:205], v[88:89], v[18:19], v[206:207]
	v_fmac_f32_e32 v2, v177, v1
	v_pk_fma_f32 v[16:17], v[86:87], v[18:19], v[16:17]
	v_fmac_f32_e32 v7, v176, v1
	v_lshlrev_b32_e32 v18, 16, v43
	v_and_b32_e32 v19, 0xffff0000, v43
	v_lshlrev_b32_e32 v1, 16, v42
	v_pk_fma_f32 v[42:43], v[112:113], v[18:19], v[20:21]
	v_fmac_f32_e32 v142, v189, v1
	v_pk_fma_f32 v[20:21], v[110:111], v[18:19], v[22:23]
	v_fmac_f32_e32 v141, v188, v1
	v_pk_fma_f32 v[22:23], v[108:109], v[18:19], v[32:33]
	v_fmac_f32_e32 v140, v187, v1
	v_pk_fma_f32 v[32:33], v[106:107], v[18:19], v[34:35]
	v_fmac_f32_e32 v139, v186, v1
	v_pk_fma_f32 v[30:31], v[104:105], v[18:19], v[30:31]
	v_fmac_f32_e32 v138, v185, v1
	v_pk_fma_f32 v[34:35], v[102:103], v[18:19], v[36:37]
	v_fmac_f32_e32 v137, v184, v1
	v_pk_fma_f32 v[28:29], v[100:101], v[18:19], v[28:29]
	v_fmac_f32_e32 v136, v183, v1
	v_pk_fma_f32 v[36:37], v[98:99], v[18:19], v[38:39]
	v_fmac_f32_e32 v135, v182, v1
	v_pk_fma_f32 v[26:27], v[96:97], v[18:19], v[26:27]
	v_fmac_f32_e32 v134, v181, v1
	v_pk_fma_f32 v[202:203], v[94:95], v[18:19], v[202:203]
	v_fmac_f32_e32 v133, v180, v1
	v_pk_fma_f32 v[24:25], v[92:93], v[18:19], v[24:25]
	v_fmac_f32_e32 v5, v179, v1
	v_pk_fma_f32 v[204:205], v[90:91], v[18:19], v[204:205]
	v_fmac_f32_e32 v2, v178, v1
	v_pk_fma_f32 v[16:17], v[88:89], v[18:19], v[16:17]
	v_fmac_f32_e32 v7, v177, v1
	v_lshlrev_b32_e32 v18, 16, v201
	v_and_b32_e32 v19, 0xffff0000, v201
	v_lshlrev_b32_e32 v1, 16, v200
; #define LAS __attribute__((address_space(3)))
; __device__ __forceinline__ float bf_lo(unsigned w) { return __uint_as_float(w << 16); }
; __device__ __forceinline__ float bf_hi(unsigned w) { return __uint_as_float(w & 0xffff0000u); }
; __device__ __forceinline__ void p2_conv_unit_prompt(Frame& F, int unit, int next_pm, const ConvW& cw, size_t src_off = WS_A, size_t dst_off = WS_CACT) {
;     ...
; #pragma unroll
;         for (int rg = 0; rg < CV_ROWS; rg += 8) {
;             unsigned w2[8], w1[8];
; #pragma unroll
;             for (int i = 0; i < 8; ++i) if (rg + i < CV_ROWS) { const LAS unsigned char* rp = S + (rg + i) * (DCONV * 2) + ((rg + i) < CW - 1 ? ringLo : ringHi);
;                 w2[i] = *(const LAS unsigned*)(rp + p * 2u); w1[i] = *(const LAS unsigned short*)(rp + q * 2u); }
; #pragma unroll
;             for (int i = 0; i < 8; ++i) if (rg + i < CV_ROWS) { const int rr = rg + i; const f32x2 vp = (f32x2){bf_lo(w2[i]), bf_hi(w2[i])}; const float vq = bf_lo(w1[i]);
; #pragma unroll
;                 for (int t = 0; t < 16; ++t) { const int j = rr - t; if (j >= 0 && j < CW) { ap[t] += wp[j] * vp; aq[t] += wq[j] * vq; } } }
;             __builtin_amdgcn_sched_barrier(0); }
	v_pk_fma_f32 v[38:39], v[112:113], v[18:19], v[20:21]
	v_fmac_f32_e32 v141, v189, v1
	v_pk_fma_f32 v[20:21], v[110:111], v[18:19], v[22:23]
	v_fmac_f32_e32 v140, v188, v1
	v_pk_fma_f32 v[22:23], v[108:109], v[18:19], v[32:33]
	v_fmac_f32_e32 v139, v187, v1
	v_pk_fma_f32 v[30:31], v[106:107], v[18:19], v[30:31]
	v_fmac_f32_e32 v138, v186, v1
	v_pk_fma_f32 v[32:33], v[104:105], v[18:19], v[34:35]
	v_fmac_f32_e32 v137, v185, v1
	v_pk_fma_f32 v[28:29], v[102:103], v[18:19], v[28:29]
	v_fmac_f32_e32 v136, v184, v1
	v_pk_fma_f32 v[34:35], v[100:101], v[18:19], v[36:37]
	v_fmac_f32_e32 v135, v183, v1
	v_pk_fma_f32 v[26:27], v[98:99], v[18:19], v[26:27]
	v_fmac_f32_e32 v134, v182, v1
	v_pk_fma_f32 v[200:201], v[96:97], v[18:19], v[202:203]
	v_fmac_f32_e32 v133, v181, v1
	v_pk_fma_f32 v[24:25], v[94:95], v[18:19], v[24:25]
	v_fmac_f32_e32 v5, v180, v1
	v_pk_fma_f32 v[202:203], v[92:93], v[18:19], v[204:205]
	v_fmac_f32_e32 v2, v179, v1
	v_pk_fma_f32 v[16:17], v[90:91], v[18:19], v[16:17]
	v_fmac_f32_e32 v7, v178, v1
	v_lshlrev_b32_e32 v18, 16, v199
	v_and_b32_e32 v19, 0xffff0000, v199
	v_lshlrev_b32_e32 v1, 16, v198
	v_pk_fma_f32 v[36:37], v[112:113], v[18:19], v[20:21]
	v_fmac_f32_e32 v140, v189, v1
	v_pk_fma_f32 v[20:21], v[110:111], v[18:19], v[22:23]
	v_fmac_f32_e32 v139, v188, v1
	v_pk_fma_f32 v[22:23], v[108:109], v[18:19], v[30:31]
	v_fmac_f32_e32 v138, v187, v1
	v_pk_fma_f32 v[30:31], v[106:107], v[18:19], v[32:33]
	v_fmac_f32_e32 v137, v186, v1
	v_pk_fma_f32 v[28:29], v[104:105], v[18:19], v[28:29]
	v_fmac_f32_e32 v136, v185, v1
	v_pk_fma_f32 v[32:33], v[102:103], v[18:19], v[34:35]
	v_fmac_f32_e32 v135, v184, v1
	v_pk_fma_f32 v[26:27], v[100:101], v[18:19], v[26:27]
	v_fmac_f32_e32 v134, v183, v1
	v_pk_fma_f32 v[198:199], v[98:99], v[18:19], v[200:201]
	v_fmac_f32_e32 v133, v182, v1
	v_pk_fma_f32 v[24:25], v[96:97], v[18:19], v[24:25]
	v_fmac_f32_e32 v5, v181, v1
	v_pk_fma_f32 v[200:201], v[94:95], v[18:19], v[202:203]
	v_fmac_f32_e32 v2, v180, v1
	v_pk_fma_f32 v[16:17], v[92:93], v[18:19], v[16:17]
	v_fmac_f32_e32 v7, v179, v1
	v_lshlrev_b32_e32 v18, 16, v165
	v_and_b32_e32 v19, 0xffff0000, v165
	v_lshlrev_b32_e32 v1, 16, v164
	v_pk_fma_f32 v[34:35], v[112:113], v[18:19], v[20:21]
	v_fmac_f32_e32 v139, v189, v1
	v_pk_fma_f32 v[20:21], v[110:111], v[18:19], v[22:23]
	v_fmac_f32_e32 v138, v188, v1
	v_pk_fma_f32 v[22:23], v[108:109], v[18:19], v[30:31]
	v_fmac_f32_e32 v137, v187, v1
	v_pk_fma_f32 v[28:29], v[106:107], v[18:19], v[28:29]
	v_fmac_f32_e32 v136, v186, v1
	v_pk_fma_f32 v[30:31], v[104:105], v[18:19], v[32:33]
	v_fmac_f32_e32 v135, v185, v1
	v_pk_fma_f32 v[26:27], v[102:103], v[18:19], v[26:27]
	v_fmac_f32_e32 v134, v184, v1
	v_pk_fma_f32 v[164:165], v[100:101], v[18:19], v[198:199]
	v_fmac_f32_e32 v133, v183, v1
	v_pk_fma_f32 v[24:25], v[98:99], v[18:19], v[24:25]
	v_fmac_f32_e32 v5, v182, v1
	v_pk_fma_f32 v[198:199], v[96:97], v[18:19], v[200:201]
	v_fmac_f32_e32 v2, v181, v1
	v_pk_fma_f32 v[16:17], v[94:95], v[18:19], v[16:17]
	v_fmac_f32_e32 v7, v180, v1
	v_lshlrev_b32_e32 v18, 16, v163
	v_and_b32_e32 v19, 0xffff0000, v163
	v_lshlrev_b32_e32 v1, 16, v162
	v_pk_fma_f32 v[32:33], v[112:113], v[18:19], v[20:21]
	v_fmac_f32_e32 v138, v189, v1
	v_pk_fma_f32 v[20:21], v[110:111], v[18:19], v[22:23]
	v_fmac_f32_e32 v137, v188, v1
	v_pk_fma_f32 v[22:23], v[108:109], v[18:19], v[28:29]
	v_fmac_f32_e32 v136, v187, v1
	v_pk_fma_f32 v[28:29], v[106:107], v[18:19], v[30:31]
	v_fmac_f32_e32 v135, v186, v1
	v_pk_fma_f32 v[26:27], v[104:105], v[18:19], v[26:27]
	v_fmac_f32_e32 v134, v185, v1
	v_pk_fma_f32 v[162:163], v[102:103], v[18:19], v[164:165]
	v_fmac_f32_e32 v133, v184, v1
	v_pk_fma_f32 v[24:25], v[100:101], v[18:19], v[24:25]
	v_fmac_f32_e32 v5, v183, v1
	v_pk_fma_f32 v[164:165], v[98:99], v[18:19], v[198:199]
	v_fmac_f32_e32 v2, v182, v1
	v_pk_fma_f32 v[16:17], v[96:97], v[18:19], v[16:17]
	v_fmac_f32_e32 v7, v181, v1
	v_lshlrev_b32_e32 v18, 16, v161
	v_and_b32_e32 v19, 0xffff0000, v161
	v_lshlrev_b32_e32 v1, 16, v160
	v_pk_fma_f32 v[30:31], v[112:113], v[18:19], v[20:21]
	v_fmac_f32_e32 v137, v189, v1
	v_pk_fma_f32 v[20:21], v[110:111], v[18:19], v[22:23]
	v_fmac_f32_e32 v136, v188, v1
	v_pk_fma_f32 v[22:23], v[108:109], v[18:19], v[28:29]
	v_fmac_f32_e32 v135, v187, v1
	v_pk_fma_f32 v[26:27], v[106:107], v[18:19], v[26:27]
	v_fmac_f32_e32 v134, v186, v1
	v_pk_fma_f32 v[160:161], v[104:105], v[18:19], v[162:163]
	v_fmac_f32_e32 v133, v185, v1
	v_pk_fma_f32 v[24:25], v[102:103], v[18:19], v[24:25]
	v_fmac_f32_e32 v5, v184, v1
	v_pk_fma_f32 v[162:163], v[100:101], v[18:19], v[164:165]
	v_fmac_f32_e32 v2, v183, v1
	v_pk_fma_f32 v[16:17], v[98:99], v[18:19], v[16:17]
	v_fmac_f32_e32 v7, v182, v1
	v_lshlrev_b32_e32 v18, 16, v159
	v_and_b32_e32 v19, 0xffff0000, v159
	v_lshlrev_b32_e32 v1, 16, v158
	v_pk_fma_f32 v[28:29], v[112:113], v[18:19], v[20:21]
	v_fmac_f32_e32 v136, v189, v1
	v_pk_fma_f32 v[20:21], v[110:111], v[18:19], v[22:23]
	v_fmac_f32_e32 v135, v188, v1
	v_pk_fma_f32 v[22:23], v[108:109], v[18:19], v[26:27]
	v_fmac_f32_e32 v134, v187, v1
	v_pk_fma_f32 v[158:159], v[106:107], v[18:19], v[160:161]
	v_fmac_f32_e32 v133, v186, v1
	v_pk_fma_f32 v[24:25], v[104:105], v[18:19], v[24:25]
	v_fmac_f32_e32 v5, v185, v1
	v_pk_fma_f32 v[160:161], v[102:103], v[18:19], v[162:163]
	v_fmac_f32_e32 v2, v184, v1
	v_pk_fma_f32 v[16:17], v[100:101], v[18:19], v[16:17]
	v_fmac_f32_e32 v7, v183, v1
	v_lshlrev_b32_e32 v18, 16, v157
	v_and_b32_e32 v19, 0xffff0000, v157
	v_lshlrev_b32_e32 v1, 16, v156
	v_pk_fma_f32 v[26:27], v[112:113], v[18:19], v[20:21]
	v_fmac_f32_e32 v135, v189, v1
	v_pk_fma_f32 v[20:21], v[110:111], v[18:19], v[22:23]
; #define LDS_WAIT() asm volatile("s_waitcnt lgkmcnt(0)" ::: "memory")
; __device__ __forceinline__ float bf_lo(unsigned w) { return __uint_as_float(w << 16); }
; __device__ __forceinline__ float bf_hi(unsigned w) { return __uint_as_float(w & 0xffff0000u); }
; template <int CTRL, int RM> __device__ __forceinline__ float dppf(float v) { return __builtin_bit_cast(float, __builtin_amdgcn_update_dpp(0, __builtin_bit_cast(int, v), CTRL, RM, 0xF, false)); }
; __device__ __forceinline__ float row_sum_dpp(float v) {
;     v += dppf<0xB1, 0xF>(v); v += dppf<0x4E, 0xF>(v); v += dppf<0x141, 0xF>(v); v += dppf<0x140, 0xF>(v); return v; }
; __device__ __forceinline__ float half_sum_dpp(float v) {
;     v = row_sum_dpp(v); v += dppf<0x142, 0xA>(v); return v; }
; __device__ __forceinline__ float wave_sum(float v) {
;     v = half_sum_dpp(v); v += dppf<0x143, 0xC>(v);
;     return __builtin_bit_cast(float, __builtin_amdgcn_readlane(__builtin_bit_cast(int, v), 63)); }
; __device__ __forceinline__ void p2_conv_unit_prompt(Frame& F, int unit, int next_pm, const ConvW& cw, size_t src_off = WS_A, size_t dst_off = WS_CACT) {
;     ...
;             for (int i = 0; i < 8; ++i) if (rg + i < CV_ROWS) { const int rr = rg + i; const f32x2 vp = (f32x2){bf_lo(w2[i]), bf_hi(w2[i])}; const float vq = bf_lo(w1[i]);
; #pragma unroll
;                 for (int t = 0; t < 16; ++t) { const int j = rr - t; if (j >= 0 && j < CW) { ap[t] += wp[j] * vp; aq[t] += wq[j] * vq; } } }
;             __builtin_amdgcn_sched_barrier(0); }
;         LDS_WAIT(); __syncthreads();
;         if (h == 0) conv_stage_tail(F, S, rowA + 16, src_off);
;         else if (next_pm >= 0) poolmix_stage(F, next_pm);
;         float st[32];
; #pragma unroll
;         for (int t = 0; t < 16; ++t) { st[t] = (ap[t].x + ap[t].y) + aq[t]; st[16 + t] = (ap[t].x * ap[t].x + ap[t].y * ap[t].y) + aq[t] * aq[t]; }
;         float tot = 0.f;
; #pragma unroll
;         for (int i = 0; i < 32; ++i) { const float w = wave_sum(st[i]); asm volatile("v_writelane_b32 %0, %1, %2" : "+v"(tot) : "s"(w), "n"(i)); }
	v_fmac_f32_e32 v134, v188, v1
	v_pk_fma_f32 v[22:23], v[108:109], v[18:19], v[158:159]
	v_fmac_f32_e32 v133, v187, v1
	v_pk_fma_f32 v[156:157], v[106:107], v[18:19], v[24:25]
	v_fmac_f32_e32 v5, v186, v1
	v_pk_fma_f32 v[158:159], v[104:105], v[18:19], v[160:161]
	v_fmac_f32_e32 v2, v185, v1
	v_pk_fma_f32 v[16:17], v[102:103], v[18:19], v[16:17]
	v_fmac_f32_e32 v7, v184, v1
	v_lshlrev_b32_e32 v18, 16, v155
	v_and_b32_e32 v19, 0xffff0000, v155
	v_lshlrev_b32_e32 v1, 16, v154
	v_pk_fma_f32 v[24:25], v[112:113], v[18:19], v[20:21]
	v_fmac_f32_e32 v134, v189, v1
	v_pk_fma_f32 v[20:21], v[110:111], v[18:19], v[22:23]
	v_fmac_f32_e32 v133, v188, v1
	v_pk_fma_f32 v[154:155], v[108:109], v[18:19], v[156:157]
	v_fmac_f32_e32 v5, v187, v1
	v_pk_fma_f32 v[156:157], v[106:107], v[18:19], v[158:159]
	v_fmac_f32_e32 v2, v186, v1
	v_pk_fma_f32 v[16:17], v[104:105], v[18:19], v[16:17]
	v_fmac_f32_e32 v7, v185, v1
	v_lshlrev_b32_e32 v18, 16, v153
	v_and_b32_e32 v19, 0xffff0000, v153
	v_lshlrev_b32_e32 v1, 16, v152
	v_pk_fma_f32 v[22:23], v[112:113], v[18:19], v[20:21]
	v_fmac_f32_e32 v133, v189, v1
	v_pk_fma_f32 v[20:21], v[110:111], v[18:19], v[154:155]
	v_fmac_f32_e32 v5, v188, v1
	v_pk_fma_f32 v[152:153], v[108:109], v[18:19], v[156:157]
	v_fmac_f32_e32 v2, v187, v1
	v_pk_fma_f32 v[16:17], v[106:107], v[18:19], v[16:17]
	v_fmac_f32_e32 v7, v186, v1
	v_lshlrev_b32_e32 v18, 16, v151
	v_and_b32_e32 v19, 0xffff0000, v151
	v_lshlrev_b32_e32 v1, 16, v150
	v_fmac_f32_e32 v5, v189, v1
	v_pk_fma_f32 v[150:151], v[110:111], v[18:19], v[152:153]
	v_fmac_f32_e32 v2, v188, v1
	v_pk_fma_f32 v[16:17], v[108:109], v[18:19], v[16:17]
	v_fmac_f32_e32 v7, v187, v1
	v_lshlrev_b32_e32 v152, 16, v149
	v_and_b32_e32 v153, 0xffff0000, v149
	v_lshlrev_b32_e32 v1, 16, v148
	v_fmac_f32_e32 v2, v189, v1
	v_pk_fma_f32 v[16:17], v[110:111], v[152:153], v[16:17]
	v_fmac_f32_e32 v7, v188, v1
	v_lshlrev_b32_e32 v148, 16, v147
	v_and_b32_e32 v149, 0xffff0000, v147
	v_lshlrev_b32_e32 v1, 16, v146
	v_pk_mul_f32 v[146:147], v[40:41], v[40:41]
	v_pk_fma_f32 v[16:17], v[112:113], v[148:149], v[16:17]
	v_add_f32_e32 v148, v146, v147
	v_add_f32_e32 v146, v46, v47
	v_add_f32_e32 v149, v144, v146
	v_pk_mul_f32 v[146:147], v[46:47], v[46:47]
	v_pk_fma_f32 v[20:21], v[112:113], v[18:19], v[20:21]
	v_pk_fma_f32 v[18:19], v[112:113], v[152:153], v[150:151]
	v_add_f32_e32 v150, v146, v147
	v_add_f32_e32 v146, v44, v45
	v_add_f32_e32 v151, v143, v146
	v_pk_mul_f32 v[146:147], v[44:45], v[44:45]
	v_fmac_f32_e32 v7, v189, v1
	v_add_f32_e32 v152, v146, v147
	v_add_f32_e32 v146, v42, v43
	v_add_f32_e32 v153, v142, v146
	v_pk_mul_f32 v[146:147], v[42:43], v[42:43]
	v_add_f32_e32 v1, v40, v41
	v_add_f32_e32 v154, v146, v147
	v_add_f32_e32 v146, v38, v39
	v_add_f32_e32 v155, v141, v146
	v_pk_mul_f32 v[146:147], v[38:39], v[38:39]
	v_add_f32_e32 v1, v145, v1
	v_add_f32_e32 v156, v146, v147
	v_add_f32_e32 v146, v36, v37
	v_add_f32_e32 v157, v140, v146
	v_pk_mul_f32 v[146:147], v[36:37], v[36:37]
	v_add_f32_dpp v1, v1, v1 quad_perm:[1,0,3,2] row_mask:0xf bank_mask:0xf bound_ctrl:1
	v_add_f32_e32 v158, v146, v147
	v_add_f32_e32 v146, v34, v35
	v_add_f32_e32 v159, v139, v146
	v_pk_mul_f32 v[146:147], v[34:35], v[34:35]
	v_add_f32_dpp v1, v1, v1 quad_perm:[2,3,0,1] row_mask:0xf bank_mask:0xf bound_ctrl:1
	v_add_f32_e32 v160, v146, v147
	v_add_f32_e32 v146, v32, v33
	v_add_f32_e32 v161, v138, v146
	v_pk_mul_f32 v[146:147], v[32:33], v[32:33]
	v_add_f32_dpp v1, v1, v1 row_half_mirror row_mask:0xf bank_mask:0xf bound_ctrl:1
	v_add_f32_e32 v162, v146, v147
	v_add_f32_e32 v146, v30, v31
	v_add_f32_e32 v163, v137, v146
	v_pk_mul_f32 v[146:147], v[30:31], v[30:31]
	v_add_f32_dpp v1, v1, v1 row_mirror row_mask:0xf bank_mask:0xf bound_ctrl:1
	v_add_f32_e32 v164, v146, v147
	v_add_f32_e32 v146, v28, v29
	v_add_f32_e32 v165, v136, v146
	v_pk_mul_f32 v[146:147], v[28:29], v[28:29]
	v_fmac_f32_e32 v148, v145, v145
	v_add_f32_e32 v198, v146, v147
	v_add_f32_e32 v146, v26, v27
	v_add_f32_e32 v199, v135, v146
	v_pk_mul_f32 v[146:147], v[26:27], v[26:27]
	v_fmac_f32_e32 v150, v144, v144
	v_add_f32_e32 v200, v146, v147
	v_add_f32_e32 v146, v24, v25
	v_add_f32_e32 v201, v134, v146
	v_pk_mul_f32 v[146:147], v[24:25], v[24:25]
	v_fmac_f32_e32 v152, v143, v143
	v_add_f32_e32 v202, v146, v147
	v_add_f32_e32 v146, v22, v23
	v_add_f32_e32 v203, v133, v146
	v_pk_mul_f32 v[146:147], v[22:23], v[22:23]
	v_fmac_f32_e32 v154, v142, v142
	v_add_f32_e32 v204, v146, v147
	v_add_f32_e32 v146, v20, v21
	v_add_f32_e32 v205, v5, v146
	v_pk_mul_f32 v[146:147], v[20:21], v[20:21]
	v_fmac_f32_e32 v156, v141, v141
	v_add_f32_e32 v206, v146, v147
	v_add_f32_e32 v146, v18, v19
	v_add_f32_e32 v207, v2, v146
	v_pk_mul_f32 v[146:147], v[18:19], v[18:19]
	v_fmac_f32_e32 v158, v140, v140
	v_add_f32_e32 v208, v146, v147
	v_add_f32_e32 v146, v16, v17
	v_add_f32_e32 v209, v7, v146
	v_pk_mul_f32 v[146:147], v[16:17], v[16:17]
	v_fmac_f32_e32 v160, v139, v139
	v_add_f32_e32 v147, v146, v147
	v_mov_b32_e32 v146, v3
	v_fmac_f32_e32 v162, v138, v138
	v_fmac_f32_e32 v164, v137, v137
	v_mov_b32_dpp v146, v1 row_bcast:15 row_mask:0xa bank_mask:0xf
	v_add_f32_e32 v1, v1, v146
	v_mov_b32_e32 v146, v3
	v_fmac_f32_e32 v198, v136, v136
	v_fmac_f32_e32 v200, v135, v135
	v_mov_b32_dpp v146, v1 row_bcast:31 row_mask:0xc bank_mask:0xf
	v_add_f32_e32 v1, v1, v146
	v_mov_b32_e32 v146, v3
	v_readlane_b32 s12, v1, 63
	v_fmac_f32_e32 v202, v134, v134
	v_fmac_f32_e32 v204, v133, v133
	v_fmac_f32_e32 v206, v5, v5
	v_fmac_f32_e32 v208, v2, v2
	v_fmac_f32_e32 v147, v7, v7
	v_writelane_b32 v146, s12, 0
	v_add_f32_dpp v149, v149, v149 quad_perm:[1,0,3,2] row_mask:0xf bank_mask:0xf bound_ctrl:1
; template <int CTRL, int RM> __device__ __forceinline__ float dppf(float v) { return __builtin_bit_cast(float, __builtin_amdgcn_update_dpp(0, __builtin_bit_cast(int, v), CTRL, RM, 0xF, false)); }
; __device__ __forceinline__ float row_sum_dpp(float v) {
;     v += dppf<0xB1, 0xF>(v); v += dppf<0x4E, 0xF>(v); v += dppf<0x141, 0xF>(v); v += dppf<0x140, 0xF>(v); return v; }
; __device__ __forceinline__ float half_sum_dpp(float v) {
;     v = row_sum_dpp(v); v += dppf<0x142, 0xA>(v); return v; }
; __device__ __forceinline__ float wave_sum(float v) {
;     v = half_sum_dpp(v); v += dppf<0x143, 0xC>(v);
;     return __builtin_bit_cast(float, __builtin_amdgcn_readlane(__builtin_bit_cast(int, v), 63)); }
; __device__ __forceinline__ void p2_conv_unit_prompt(Frame& F, int unit, int next_pm, const ConvW& cw, size_t src_off = WS_A, size_t dst_off = WS_CACT) {
;     ...
;         for (int i = 0; i < 32; ++i) { const float w = wave_sum(st[i]); asm volatile("v_writelane_b32 %0, %1, %2" : "+v"(tot) : "s"(w), "n"(i)); }
	v_add_f32_dpp v151, v151, v151 quad_perm:[1,0,3,2] row_mask:0xf bank_mask:0xf bound_ctrl:1
	v_add_f32_dpp v153, v153, v153 quad_perm:[1,0,3,2] row_mask:0xf bank_mask:0xf bound_ctrl:1
	v_add_f32_dpp v155, v155, v155 quad_perm:[1,0,3,2] row_mask:0xf bank_mask:0xf bound_ctrl:1
	v_add_f32_dpp v157, v157, v157 quad_perm:[1,0,3,2] row_mask:0xf bank_mask:0xf bound_ctrl:1
	v_add_f32_dpp v159, v159, v159 quad_perm:[1,0,3,2] row_mask:0xf bank_mask:0xf bound_ctrl:1
	v_add_f32_dpp v161, v161, v161 quad_perm:[1,0,3,2] row_mask:0xf bank_mask:0xf bound_ctrl:1
	v_add_f32_dpp v163, v163, v163 quad_perm:[1,0,3,2] row_mask:0xf bank_mask:0xf bound_ctrl:1
	v_add_f32_dpp v165, v165, v165 quad_perm:[1,0,3,2] row_mask:0xf bank_mask:0xf bound_ctrl:1
	v_add_f32_dpp v199, v199, v199 quad_perm:[1,0,3,2] row_mask:0xf bank_mask:0xf bound_ctrl:1
	v_add_f32_dpp v201, v201, v201 quad_perm:[1,0,3,2] row_mask:0xf bank_mask:0xf bound_ctrl:1
	v_add_f32_dpp v203, v203, v203 quad_perm:[1,0,3,2] row_mask:0xf bank_mask:0xf bound_ctrl:1
	v_add_f32_dpp v205, v205, v205 quad_perm:[1,0,3,2] row_mask:0xf bank_mask:0xf bound_ctrl:1
	v_add_f32_dpp v207, v207, v207 quad_perm:[1,0,3,2] row_mask:0xf bank_mask:0xf bound_ctrl:1
	v_add_f32_dpp v209, v209, v209 quad_perm:[1,0,3,2] row_mask:0xf bank_mask:0xf bound_ctrl:1
	v_add_f32_dpp v148, v148, v148 quad_perm:[1,0,3,2] row_mask:0xf bank_mask:0xf bound_ctrl:1
	v_add_f32_dpp v150, v150, v150 quad_perm:[1,0,3,2] row_mask:0xf bank_mask:0xf bound_ctrl:1
	v_add_f32_dpp v152, v152, v152 quad_perm:[1,0,3,2] row_mask:0xf bank_mask:0xf bound_ctrl:1
	v_add_f32_dpp v154, v154, v154 quad_perm:[1,0,3,2] row_mask:0xf bank_mask:0xf bound_ctrl:1
	v_add_f32_dpp v156, v156, v156 quad_perm:[1,0,3,2] row_mask:0xf bank_mask:0xf bound_ctrl:1
	v_add_f32_dpp v158, v158, v158 quad_perm:[1,0,3,2] row_mask:0xf bank_mask:0xf bound_ctrl:1
	v_add_f32_dpp v160, v160, v160 quad_perm:[1,0,3,2] row_mask:0xf bank_mask:0xf bound_ctrl:1
	v_add_f32_dpp v162, v162, v162 quad_perm:[1,0,3,2] row_mask:0xf bank_mask:0xf bound_ctrl:1
	v_add_f32_dpp v164, v164, v164 quad_perm:[1,0,3,2] row_mask:0xf bank_mask:0xf bound_ctrl:1
	v_add_f32_dpp v198, v198, v198 quad_perm:[1,0,3,2] row_mask:0xf bank_mask:0xf bound_ctrl:1
	v_add_f32_dpp v200, v200, v200 quad_perm:[1,0,3,2] row_mask:0xf bank_mask:0xf bound_ctrl:1
	v_add_f32_dpp v202, v202, v202 quad_perm:[1,0,3,2] row_mask:0xf bank_mask:0xf bound_ctrl:1
	v_add_f32_dpp v204, v204, v204 quad_perm:[1,0,3,2] row_mask:0xf bank_mask:0xf bound_ctrl:1
	v_add_f32_dpp v206, v206, v206 quad_perm:[1,0,3,2] row_mask:0xf bank_mask:0xf bound_ctrl:1
	v_add_f32_dpp v208, v208, v208 quad_perm:[1,0,3,2] row_mask:0xf bank_mask:0xf bound_ctrl:1
	v_add_f32_dpp v147, v147, v147 quad_perm:[1,0,3,2] row_mask:0xf bank_mask:0xf bound_ctrl:1
	v_add_f32_dpp v149, v149, v149 quad_perm:[2,3,0,1] row_mask:0xf bank_mask:0xf bound_ctrl:1
	v_add_f32_dpp v151, v151, v151 quad_perm:[2,3,0,1] row_mask:0xf bank_mask:0xf bound_ctrl:1
	v_add_f32_dpp v153, v153, v153 quad_perm:[2,3,0,1] row_mask:0xf bank_mask:0xf bound_ctrl:1
	v_add_f32_dpp v155, v155, v155 quad_perm:[2,3,0,1] row_mask:0xf bank_mask:0xf bound_ctrl:1
	v_add_f32_dpp v157, v157, v157 quad_perm:[2,3,0,1] row_mask:0xf bank_mask:0xf bound_ctrl:1
	v_add_f32_dpp v159, v159, v159 quad_perm:[2,3,0,1] row_mask:0xf bank_mask:0xf bound_ctrl:1
	v_add_f32_dpp v161, v161, v161 quad_perm:[2,3,0,1] row_mask:0xf bank_mask:0xf bound_ctrl:1
	v_add_f32_dpp v163, v163, v163 quad_perm:[2,3,0,1] row_mask:0xf bank_mask:0xf bound_ctrl:1
	v_add_f32_dpp v165, v165, v165 quad_perm:[2,3,0,1] row_mask:0xf bank_mask:0xf bound_ctrl:1
	v_add_f32_dpp v199, v199, v199 quad_perm:[2,3,0,1] row_mask:0xf bank_mask:0xf bound_ctrl:1
	v_add_f32_dpp v201, v201, v201 quad_perm:[2,3,0,1] row_mask:0xf bank_mask:0xf bound_ctrl:1
	v_add_f32_dpp v203, v203, v203 quad_perm:[2,3,0,1] row_mask:0xf bank_mask:0xf bound_ctrl:1
	v_add_f32_dpp v205, v205, v205 quad_perm:[2,3,0,1] row_mask:0xf bank_mask:0xf bound_ctrl:1
	v_add_f32_dpp v207, v207, v207 quad_perm:[2,3,0,1] row_mask:0xf bank_mask:0xf bound_ctrl:1
	v_add_f32_dpp v209, v209, v209 quad_perm:[2,3,0,1] row_mask:0xf bank_mask:0xf bound_ctrl:1
	v_add_f32_dpp v148, v148, v148 quad_perm:[2,3,0,1] row_mask:0xf bank_mask:0xf bound_ctrl:1
	v_add_f32_dpp v150, v150, v150 quad_perm:[2,3,0,1] row_mask:0xf bank_mask:0xf bound_ctrl:1
	v_add_f32_dpp v152, v152, v152 quad_perm:[2,3,0,1] row_mask:0xf bank_mask:0xf bound_ctrl:1
	v_add_f32_dpp v154, v154, v154 quad_perm:[2,3,0,1] row_mask:0xf bank_mask:0xf bound_ctrl:1
	v_add_f32_dpp v156, v156, v156 quad_perm:[2,3,0,1] row_mask:0xf bank_mask:0xf bound_ctrl:1
	v_add_f32_dpp v158, v158, v158 quad_perm:[2,3,0,1] row_mask:0xf bank_mask:0xf bound_ctrl:1
	v_add_f32_dpp v160, v160, v160 quad_perm:[2,3,0,1] row_mask:0xf bank_mask:0xf bound_ctrl:1
	v_add_f32_dpp v162, v162, v162 quad_perm:[2,3,0,1] row_mask:0xf bank_mask:0xf bound_ctrl:1
	v_add_f32_dpp v164, v164, v164 quad_perm:[2,3,0,1] row_mask:0xf bank_mask:0xf bound_ctrl:1
	v_add_f32_dpp v198, v198, v198 quad_perm:[2,3,0,1] row_mask:0xf bank_mask:0xf bound_ctrl:1
	v_add_f32_dpp v200, v200, v200 quad_perm:[2,3,0,1] row_mask:0xf bank_mask:0xf bound_ctrl:1
	v_add_f32_dpp v202, v202, v202 quad_perm:[2,3,0,1] row_mask:0xf bank_mask:0xf bound_ctrl:1
	v_add_f32_dpp v204, v204, v204 quad_perm:[2,3,0,1] row_mask:0xf bank_mask:0xf bound_ctrl:1
	v_add_f32_dpp v206, v206, v206 quad_perm:[2,3,0,1] row_mask:0xf bank_mask:0xf bound_ctrl:1
	v_add_f32_dpp v208, v208, v208 quad_perm:[2,3,0,1] row_mask:0xf bank_mask:0xf bound_ctrl:1
	v_add_f32_dpp v147, v147, v147 quad_perm:[2,3,0,1] row_mask:0xf bank_mask:0xf bound_ctrl:1
; template <int CTRL, int RM> __device__ __forceinline__ float dppf(float v) { return __builtin_bit_cast(float, __builtin_amdgcn_update_dpp(0, __builtin_bit_cast(int, v), CTRL, RM, 0xF, false)); }
; __device__ __forceinline__ float row_sum_dpp(float v) {
;     v += dppf<0xB1, 0xF>(v); v += dppf<0x4E, 0xF>(v); v += dppf<0x141, 0xF>(v); v += dppf<0x140, 0xF>(v); return v; }
; __device__ __forceinline__ float half_sum_dpp(float v) {
;     v = row_sum_dpp(v); v += dppf<0x142, 0xA>(v); return v; }
; __device__ __forceinline__ float wave_sum(float v) {
;     v = half_sum_dpp(v); v += dppf<0x143, 0xC>(v);
;     return __builtin_bit_cast(float, __builtin_amdgcn_readlane(__builtin_bit_cast(int, v), 63)); }
; __device__ __forceinline__ void p2_conv_unit_prompt(Frame& F, int unit, int next_pm, const ConvW& cw, size_t src_off = WS_A, size_t dst_off = WS_CACT) {
;     ...
;         for (int i = 0; i < 32; ++i) { const float w = wave_sum(st[i]); asm volatile("v_writelane_b32 %0, %1, %2" : "+v"(tot) : "s"(w), "n"(i)); }
	v_add_f32_dpp v149, v149, v149 row_half_mirror row_mask:0xf bank_mask:0xf bound_ctrl:1
	v_add_f32_dpp v151, v151, v151 row_half_mirror row_mask:0xf bank_mask:0xf bound_ctrl:1
	v_add_f32_dpp v153, v153, v153 row_half_mirror row_mask:0xf bank_mask:0xf bound_ctrl:1
	v_add_f32_dpp v155, v155, v155 row_half_mirror row_mask:0xf bank_mask:0xf bound_ctrl:1
	v_add_f32_dpp v157, v157, v157 row_half_mirror row_mask:0xf bank_mask:0xf bound_ctrl:1
	v_add_f32_dpp v159, v159, v159 row_half_mirror row_mask:0xf bank_mask:0xf bound_ctrl:1
	v_add_f32_dpp v161, v161, v161 row_half_mirror row_mask:0xf bank_mask:0xf bound_ctrl:1
	v_add_f32_dpp v163, v163, v163 row_half_mirror row_mask:0xf bank_mask:0xf bound_ctrl:1
	v_add_f32_dpp v165, v165, v165 row_half_mirror row_mask:0xf bank_mask:0xf bound_ctrl:1
	v_add_f32_dpp v199, v199, v199 row_half_mirror row_mask:0xf bank_mask:0xf bound_ctrl:1
	v_add_f32_dpp v201, v201, v201 row_half_mirror row_mask:0xf bank_mask:0xf bound_ctrl:1
	v_add_f32_dpp v203, v203, v203 row_half_mirror row_mask:0xf bank_mask:0xf bound_ctrl:1
	v_add_f32_dpp v205, v205, v205 row_half_mirror row_mask:0xf bank_mask:0xf bound_ctrl:1
	v_add_f32_dpp v207, v207, v207 row_half_mirror row_mask:0xf bank_mask:0xf bound_ctrl:1
	v_add_f32_dpp v209, v209, v209 row_half_mirror row_mask:0xf bank_mask:0xf bound_ctrl:1
	v_add_f32_dpp v148, v148, v148 row_half_mirror row_mask:0xf bank_mask:0xf bound_ctrl:1
	v_add_f32_dpp v150, v150, v150 row_half_mirror row_mask:0xf bank_mask:0xf bound_ctrl:1
	v_add_f32_dpp v152, v152, v152 row_half_mirror row_mask:0xf bank_mask:0xf bound_ctrl:1
	v_add_f32_dpp v154, v154, v154 row_half_mirror row_mask:0xf bank_mask:0xf bound_ctrl:1
	v_add_f32_dpp v156, v156, v156 row_half_mirror row_mask:0xf bank_mask:0xf bound_ctrl:1
	v_add_f32_dpp v158, v158, v158 row_half_mirror row_mask:0xf bank_mask:0xf bound_ctrl:1
	v_add_f32_dpp v160, v160, v160 row_half_mirror row_mask:0xf bank_mask:0xf bound_ctrl:1
	v_add_f32_dpp v162, v162, v162 row_half_mirror row_mask:0xf bank_mask:0xf bound_ctrl:1
	v_add_f32_dpp v164, v164, v164 row_half_mirror row_mask:0xf bank_mask:0xf bound_ctrl:1
	v_add_f32_dpp v198, v198, v198 row_half_mirror row_mask:0xf bank_mask:0xf bound_ctrl:1
	v_add_f32_dpp v200, v200, v200 row_half_mirror row_mask:0xf bank_mask:0xf bound_ctrl:1
	v_add_f32_dpp v202, v202, v202 row_half_mirror row_mask:0xf bank_mask:0xf bound_ctrl:1
	v_add_f32_dpp v204, v204, v204 row_half_mirror row_mask:0xf bank_mask:0xf bound_ctrl:1
	v_add_f32_dpp v206, v206, v206 row_half_mirror row_mask:0xf bank_mask:0xf bound_ctrl:1
	v_add_f32_dpp v208, v208, v208 row_half_mirror row_mask:0xf bank_mask:0xf bound_ctrl:1
	v_add_f32_dpp v147, v147, v147 row_half_mirror row_mask:0xf bank_mask:0xf bound_ctrl:1
	v_add_f32_dpp v149, v149, v149 row_mirror row_mask:0xf bank_mask:0xf bound_ctrl:1
	v_add_f32_dpp v151, v151, v151 row_mirror row_mask:0xf bank_mask:0xf bound_ctrl:1
	v_add_f32_dpp v153, v153, v153 row_mirror row_mask:0xf bank_mask:0xf bound_ctrl:1
	v_add_f32_dpp v155, v155, v155 row_mirror row_mask:0xf bank_mask:0xf bound_ctrl:1
	v_add_f32_dpp v157, v157, v157 row_mirror row_mask:0xf bank_mask:0xf bound_ctrl:1
	v_add_f32_dpp v159, v159, v159 row_mirror row_mask:0xf bank_mask:0xf bound_ctrl:1
	v_add_f32_dpp v161, v161, v161 row_mirror row_mask:0xf bank_mask:0xf bound_ctrl:1
	v_add_f32_dpp v163, v163, v163 row_mirror row_mask:0xf bank_mask:0xf bound_ctrl:1
	v_add_f32_dpp v165, v165, v165 row_mirror row_mask:0xf bank_mask:0xf bound_ctrl:1
	v_add_f32_dpp v199, v199, v199 row_mirror row_mask:0xf bank_mask:0xf bound_ctrl:1
	v_add_f32_dpp v201, v201, v201 row_mirror row_mask:0xf bank_mask:0xf bound_ctrl:1
	v_add_f32_dpp v203, v203, v203 row_mirror row_mask:0xf bank_mask:0xf bound_ctrl:1
	v_add_f32_dpp v205, v205, v205 row_mirror row_mask:0xf bank_mask:0xf bound_ctrl:1
	v_add_f32_dpp v207, v207, v207 row_mirror row_mask:0xf bank_mask:0xf bound_ctrl:1
	v_add_f32_dpp v209, v209, v209 row_mirror row_mask:0xf bank_mask:0xf bound_ctrl:1
	v_add_f32_dpp v148, v148, v148 row_mirror row_mask:0xf bank_mask:0xf bound_ctrl:1
	v_add_f32_dpp v150, v150, v150 row_mirror row_mask:0xf bank_mask:0xf bound_ctrl:1
	v_add_f32_dpp v152, v152, v152 row_mirror row_mask:0xf bank_mask:0xf bound_ctrl:1
	v_add_f32_dpp v154, v154, v154 row_mirror row_mask:0xf bank_mask:0xf bound_ctrl:1
	v_add_f32_dpp v156, v156, v156 row_mirror row_mask:0xf bank_mask:0xf bound_ctrl:1
	v_add_f32_dpp v158, v158, v158 row_mirror row_mask:0xf bank_mask:0xf bound_ctrl:1
	v_add_f32_dpp v160, v160, v160 row_mirror row_mask:0xf bank_mask:0xf bound_ctrl:1
	v_add_f32_dpp v162, v162, v162 row_mirror row_mask:0xf bank_mask:0xf bound_ctrl:1
	v_add_f32_dpp v164, v164, v164 row_mirror row_mask:0xf bank_mask:0xf bound_ctrl:1
	v_add_f32_dpp v198, v198, v198 row_mirror row_mask:0xf bank_mask:0xf bound_ctrl:1
	v_add_f32_dpp v200, v200, v200 row_mirror row_mask:0xf bank_mask:0xf bound_ctrl:1
	v_add_f32_dpp v202, v202, v202 row_mirror row_mask:0xf bank_mask:0xf bound_ctrl:1
	v_add_f32_dpp v204, v204, v204 row_mirror row_mask:0xf bank_mask:0xf bound_ctrl:1
	v_add_f32_dpp v206, v206, v206 row_mirror row_mask:0xf bank_mask:0xf bound_ctrl:1
	v_add_f32_dpp v208, v208, v208 row_mirror row_mask:0xf bank_mask:0xf bound_ctrl:1
	v_add_f32_dpp v147, v147, v147 row_mirror row_mask:0xf bank_mask:0xf bound_ctrl:1
	v_add_f32_dpp v149, v149, v149 row_bcast:15 row_mask:0xa bank_mask:0xf
	v_add_f32_dpp v151, v151, v151 row_bcast:15 row_mask:0xa bank_mask:0xf
	v_add_f32_dpp v153, v153, v153 row_bcast:15 row_mask:0xa bank_mask:0xf
	v_add_f32_dpp v155, v155, v155 row_bcast:15 row_mask:0xa bank_mask:0xf
	v_add_f32_dpp v157, v157, v157 row_bcast:15 row_mask:0xa bank_mask:0xf
; template <int CTRL, int RM> __device__ __forceinline__ float dppf(float v) { return __builtin_bit_cast(float, __builtin_amdgcn_update_dpp(0, __builtin_bit_cast(int, v), CTRL, RM, 0xF, false)); }
; __device__ __forceinline__ float row_sum_dpp(float v) {
;     v += dppf<0xB1, 0xF>(v); v += dppf<0x4E, 0xF>(v); v += dppf<0x141, 0xF>(v); v += dppf<0x140, 0xF>(v); return v; }
; __device__ __forceinline__ float half_sum_dpp(float v) {
;     v = row_sum_dpp(v); v += dppf<0x142, 0xA>(v); return v; }
; __device__ __forceinline__ float wave_sum(float v) {
;     v = half_sum_dpp(v); v += dppf<0x143, 0xC>(v);
;     return __builtin_bit_cast(float, __builtin_amdgcn_readlane(__builtin_bit_cast(int, v), 63)); }
; __device__ __forceinline__ void p2_conv_unit_prompt(Frame& F, int unit, int next_pm, const ConvW& cw, size_t src_off = WS_A, size_t dst_off = WS_CACT) {
;     ...
;         for (int i = 0; i < 32; ++i) { const float w = wave_sum(st[i]); asm volatile("v_writelane_b32 %0, %1, %2" : "+v"(tot) : "s"(w), "n"(i)); }
;         if (ln < 32u) WPT[F.wave * 32 + (int)ln] = tot;
	v_add_f32_dpp v159, v159, v159 row_bcast:15 row_mask:0xa bank_mask:0xf
	v_add_f32_dpp v161, v161, v161 row_bcast:15 row_mask:0xa bank_mask:0xf
	v_add_f32_dpp v163, v163, v163 row_bcast:15 row_mask:0xa bank_mask:0xf
	v_add_f32_dpp v165, v165, v165 row_bcast:15 row_mask:0xa bank_mask:0xf
	v_add_f32_dpp v199, v199, v199 row_bcast:15 row_mask:0xa bank_mask:0xf
	v_add_f32_dpp v201, v201, v201 row_bcast:15 row_mask:0xa bank_mask:0xf
	v_add_f32_dpp v203, v203, v203 row_bcast:15 row_mask:0xa bank_mask:0xf
	v_add_f32_dpp v205, v205, v205 row_bcast:15 row_mask:0xa bank_mask:0xf
	v_add_f32_dpp v207, v207, v207 row_bcast:15 row_mask:0xa bank_mask:0xf
	v_add_f32_dpp v209, v209, v209 row_bcast:15 row_mask:0xa bank_mask:0xf
	v_add_f32_dpp v148, v148, v148 row_bcast:15 row_mask:0xa bank_mask:0xf
	v_add_f32_dpp v150, v150, v150 row_bcast:15 row_mask:0xa bank_mask:0xf
	v_add_f32_dpp v152, v152, v152 row_bcast:15 row_mask:0xa bank_mask:0xf
	v_add_f32_dpp v154, v154, v154 row_bcast:15 row_mask:0xa bank_mask:0xf
	v_add_f32_dpp v156, v156, v156 row_bcast:15 row_mask:0xa bank_mask:0xf
	v_add_f32_dpp v158, v158, v158 row_bcast:15 row_mask:0xa bank_mask:0xf
	v_add_f32_dpp v160, v160, v160 row_bcast:15 row_mask:0xa bank_mask:0xf
	v_add_f32_dpp v162, v162, v162 row_bcast:15 row_mask:0xa bank_mask:0xf
	v_add_f32_dpp v164, v164, v164 row_bcast:15 row_mask:0xa bank_mask:0xf
	v_add_f32_dpp v198, v198, v198 row_bcast:15 row_mask:0xa bank_mask:0xf
	v_add_f32_dpp v200, v200, v200 row_bcast:15 row_mask:0xa bank_mask:0xf
	v_add_f32_dpp v202, v202, v202 row_bcast:15 row_mask:0xa bank_mask:0xf
	v_add_f32_dpp v204, v204, v204 row_bcast:15 row_mask:0xa bank_mask:0xf
	v_add_f32_dpp v206, v206, v206 row_bcast:15 row_mask:0xa bank_mask:0xf
	v_add_f32_dpp v208, v208, v208 row_bcast:15 row_mask:0xa bank_mask:0xf
	v_add_f32_dpp v147, v147, v147 row_bcast:15 row_mask:0xa bank_mask:0xf
	v_add_f32_dpp v149, v149, v149 row_bcast:31 row_mask:0xc bank_mask:0xf
	v_add_f32_dpp v151, v151, v151 row_bcast:31 row_mask:0xc bank_mask:0xf
	v_add_f32_dpp v153, v153, v153 row_bcast:31 row_mask:0xc bank_mask:0xf
	v_add_f32_dpp v155, v155, v155 row_bcast:31 row_mask:0xc bank_mask:0xf
	v_add_f32_dpp v157, v157, v157 row_bcast:31 row_mask:0xc bank_mask:0xf
	v_add_f32_dpp v159, v159, v159 row_bcast:31 row_mask:0xc bank_mask:0xf
	v_add_f32_dpp v161, v161, v161 row_bcast:31 row_mask:0xc bank_mask:0xf
	v_add_f32_dpp v163, v163, v163 row_bcast:31 row_mask:0xc bank_mask:0xf
	v_add_f32_dpp v165, v165, v165 row_bcast:31 row_mask:0xc bank_mask:0xf
	v_add_f32_dpp v199, v199, v199 row_bcast:31 row_mask:0xc bank_mask:0xf
	v_add_f32_dpp v201, v201, v201 row_bcast:31 row_mask:0xc bank_mask:0xf
	v_add_f32_dpp v203, v203, v203 row_bcast:31 row_mask:0xc bank_mask:0xf
	v_add_f32_dpp v205, v205, v205 row_bcast:31 row_mask:0xc bank_mask:0xf
	v_add_f32_dpp v207, v207, v207 row_bcast:31 row_mask:0xc bank_mask:0xf
	v_add_f32_dpp v209, v209, v209 row_bcast:31 row_mask:0xc bank_mask:0xf
	v_add_f32_dpp v148, v148, v148 row_bcast:31 row_mask:0xc bank_mask:0xf
	v_add_f32_dpp v150, v150, v150 row_bcast:31 row_mask:0xc bank_mask:0xf
	v_add_f32_dpp v152, v152, v152 row_bcast:31 row_mask:0xc bank_mask:0xf
	v_add_f32_dpp v154, v154, v154 row_bcast:31 row_mask:0xc bank_mask:0xf
	v_add_f32_dpp v156, v156, v156 row_bcast:31 row_mask:0xc bank_mask:0xf
	v_add_f32_dpp v158, v158, v158 row_bcast:31 row_mask:0xc bank_mask:0xf
	v_add_f32_dpp v160, v160, v160 row_bcast:31 row_mask:0xc bank_mask:0xf
	v_add_f32_dpp v162, v162, v162 row_bcast:31 row_mask:0xc bank_mask:0xf
	v_add_f32_dpp v164, v164, v164 row_bcast:31 row_mask:0xc bank_mask:0xf
	v_add_f32_dpp v198, v198, v198 row_bcast:31 row_mask:0xc bank_mask:0xf
	v_add_f32_dpp v200, v200, v200 row_bcast:31 row_mask:0xc bank_mask:0xf
	v_add_f32_dpp v202, v202, v202 row_bcast:31 row_mask:0xc bank_mask:0xf
	v_add_f32_dpp v204, v204, v204 row_bcast:31 row_mask:0xc bank_mask:0xf
	v_add_f32_dpp v206, v206, v206 row_bcast:31 row_mask:0xc bank_mask:0xf
	v_add_f32_dpp v208, v208, v208 row_bcast:31 row_mask:0xc bank_mask:0xf
	v_add_f32_dpp v147, v147, v147 row_bcast:31 row_mask:0xc bank_mask:0xf
	v_readlane_b32 s98, v149, 63
	v_readlane_b32 s99, v151, 63
	v_readlane_b32 s100, v153, 63
	v_readlane_b32 s101, v155, 63
	v_writelane_b32 v146, s98, 1
	v_writelane_b32 v146, s99, 2
	v_writelane_b32 v146, s100, 3
	v_writelane_b32 v146, s101, 4
	v_readlane_b32 s98, v157, 63
	v_readlane_b32 s99, v159, 63
	v_readlane_b32 s100, v161, 63
	v_readlane_b32 s101, v163, 63
	v_writelane_b32 v146, s98, 5
	v_writelane_b32 v146, s99, 6
	v_writelane_b32 v146, s100, 7
	v_writelane_b32 v146, s101, 8
	v_readlane_b32 s98, v165, 63
	v_readlane_b32 s99, v199, 63
	v_readlane_b32 s100, v201, 63
	v_readlane_b32 s101, v203, 63
	v_writelane_b32 v146, s98, 9
	v_writelane_b32 v146, s99, 10
	v_writelane_b32 v146, s100, 11
	v_writelane_b32 v146, s101, 12
	v_readlane_b32 s98, v205, 63
	v_readlane_b32 s99, v207, 63
	v_readlane_b32 s100, v209, 63
	v_readlane_b32 s101, v148, 63
	v_writelane_b32 v146, s98, 13
	v_writelane_b32 v146, s99, 14
	v_writelane_b32 v146, s100, 15
	v_writelane_b32 v146, s101, 16
	v_readlane_b32 s98, v150, 63
	v_readlane_b32 s99, v152, 63
	v_readlane_b32 s100, v154, 63
	v_readlane_b32 s101, v156, 63
	v_writelane_b32 v146, s98, 17
	v_writelane_b32 v146, s99, 18
	v_writelane_b32 v146, s100, 19
	v_writelane_b32 v146, s101, 20
	v_readlane_b32 s98, v158, 63
	v_readlane_b32 s99, v160, 63
	v_readlane_b32 s100, v162, 63
	v_readlane_b32 s101, v164, 63
	v_writelane_b32 v146, s98, 21
	v_writelane_b32 v146, s99, 22
	v_writelane_b32 v146, s100, 23
	v_writelane_b32 v146, s101, 24
	v_readlane_b32 s98, v198, 63
	v_readlane_b32 s99, v200, 63
	v_readlane_b32 s100, v202, 63
	v_readlane_b32 s101, v204, 63
	v_writelane_b32 v146, s98, 25
	v_writelane_b32 v146, s99, 26
	v_writelane_b32 v146, s100, 27
	v_writelane_b32 v146, s101, 28
	v_readlane_b32 s98, v206, 63
	v_readlane_b32 s99, v208, 63
	v_readlane_b32 s100, v147, 63
	v_writelane_b32 v146, s98, 29
	v_writelane_b32 v146, s99, 30
	v_writelane_b32 v146, s100, 31
	v_mov_b32_e32 v149, v3
	s_and_saveexec_b64 s[12:13], s[10:11]
	ds_write_b32 v132, v146
	s_or_b64 exec, exec, s[12:13]
	s_waitcnt lgkmcnt(0)
	s_waitcnt vmcnt(0) lgkmcnt(0)
	s_barrier
; __device__ __forceinline__ void p2_conv_unit_prompt(Frame& F, int unit, int next_pm, const ConvW& cw, size_t src_off = WS_A, size_t dst_off = WS_CACT) {
;     ...
;         if (F.tid < 16) { float s1 = 0.f, s2 = 0.f;
; #pragma unroll
;             for (int w = 0; w < 8; ++w) { s1 += WPT[w * 32 + F.tid]; s2 += WPT[w * 32 + 16 + F.tid]; }
;             const float mean = s1 * (1.0f / DCONV), var = fmaxf(s2 * (1.0f / DCONV) - mean * mean, 0.f);
;             MR[2 * F.tid] = mean; MR[2 * F.tid + 1] = 1.0f / sqrtf(var + EPS); }
	s_and_saveexec_b64 s[42:43], s[6:7]
	s_cbranch_execz .LBB0_465
	ds_read_b32 v1, v15
	ds_read_b32 v146, v48
	ds_read_b32 v147, v49
	ds_read_b32 v148, v50
	ds_read_b32 v149, v51
	ds_read_b32 v150, v52
	ds_read_b32 v151, v53
	ds_read_b32 v152, v54
	s_waitcnt lgkmcnt(7)
	v_add_f32_e32 v1, 0, v1
	s_waitcnt lgkmcnt(6)
	v_add_f32_e32 v146, 0, v146
	s_waitcnt lgkmcnt(5)
	v_add_f32_e32 v1, v1, v147
	s_waitcnt lgkmcnt(4)
	v_add_f32_e32 v146, v146, v148
	s_waitcnt lgkmcnt(3)
	v_add_f32_e32 v1, v1, v149
	s_waitcnt lgkmcnt(2)
	v_add_f32_e32 v146, v146, v150
	s_waitcnt lgkmcnt(1)
	v_add_f32_e32 v1, v1, v151
	s_waitcnt lgkmcnt(0)
	v_add_f32_e32 v146, v146, v152
	ds_read_b32 v147, v55
	ds_read_b32 v148, v56
	ds_read_b32 v149, v57
	ds_read_b32 v150, v122
	ds_read_b32 v151, v123
	ds_read_b32 v152, v124
	ds_read_b32 v153, v125
	ds_read_b32 v154, v126
	s_waitcnt lgkmcnt(7)
	v_add_f32_e32 v1, v1, v147
	s_waitcnt lgkmcnt(6)
	v_add_f32_e32 v146, v146, v148
	s_waitcnt lgkmcnt(5)
	v_add_f32_e32 v1, v1, v149
	s_waitcnt lgkmcnt(4)
	v_add_f32_e32 v146, v146, v150
	s_waitcnt lgkmcnt(3)
	v_add_f32_e32 v1, v1, v151
	s_waitcnt lgkmcnt(2)
	v_add_f32_e32 v146, v146, v152
	s_waitcnt lgkmcnt(1)
	v_add_f32_e32 v1, v1, v153
	s_waitcnt lgkmcnt(0)
	v_add_f32_e32 v147, v146, v154
	v_mul_f32_e32 v146, 0x3a2aaaab, v1
	v_mul_f32_e32 v1, v146, v146
	v_fma_f32 v1, v147, s55, -v1
	v_max_f32_e32 v1, 0, v1
	v_add_f32_e32 v1, 0x358637bd, v1
	v_mul_f32_e32 v147, 0x4f800000, v1
	v_cmp_gt_f32_e32 vcc, s56, v1
	s_nop 1
	v_cndmask_b32_e32 v1, v1, v147, vcc
	v_sqrt_f32_e32 v147, v1
	s_nop 0
	v_add_u32_e32 v148, -1, v147
	v_fma_f32 v149, -v148, v147, v1
	v_cmp_ge_f32_e64 s[12:13], 0, v149
	v_add_u32_e32 v149, 1, v147
	s_nop 0
	v_cndmask_b32_e64 v148, v147, v148, s[12:13]
	v_fma_f32 v147, -v149, v147, v1
	v_cmp_lt_f32_e64 s[12:13], 0, v147
	s_nop 1
	v_cndmask_b32_e64 v147, v148, v149, s[12:13]
	v_mul_f32_e32 v148, 0x37800000, v147
	v_cndmask_b32_e32 v147, v147, v148, vcc
	v_cmp_class_f32_e32 vcc, v1, v128
	s_nop 1
	v_cndmask_b32_e32 v1, v147, v1, vcc
	v_div_scale_f32 v147, s[12:13], v1, v1, 1.0
	v_rcp_f32_e32 v148, v147
	s_nop 0
	v_fma_f32 v149, -v147, v148, 1.0
	v_fmac_f32_e32 v148, v149, v148
	v_div_scale_f32 v149, vcc, 1.0, v1, 1.0
	v_mul_f32_e32 v150, v149, v148
	v_fma_f32 v151, -v147, v150, v149
	v_fmac_f32_e32 v150, v151, v148
	v_fma_f32 v147, -v147, v150, v149
	v_div_fmas_f32 v147, v147, v148, v150
	v_div_fixup_f32 v147, v147, v1, 1.0
	ds_write_b64 v127, v[146:147]
	s_branch .LBB0_465
